# pass A: loop-invariant triangular masks and LDS addresses hoisted out of the unit loop into spare VGPRs (v_and/v_bfi instead of add+cmp+cndmask)
# speedup vs baseline: 1.0063x; 1.0063x over previous
.LBB0_661:
	v_writelane_b32 v233, s72, 28
	s_add_u32 s10, s86, 0x16b00000
	s_addc_u32 s11, s87, 0
	v_writelane_b32 v233, s73, 29
	v_writelane_b32 v233, s57, 30
	v_writelane_b32 v233, s71, 31
	s_add_u32 s0, s86, 0x1cd00000
	v_writelane_b32 v233, s0, 32
	s_addc_u32 s0, s87, 0
	v_writelane_b32 v233, s0, 33
	s_add_u32 s0, s84, 0x2000000
	s_addc_u32 s1, s85, 0
	s_add_u32 s50, s86, 0x1f700000
	v_writelane_b32 v233, s0, 34
	s_addc_u32 s51, s87, 0
	s_mov_b32 s73, 0x5040100
	v_writelane_b32 v233, s1, 35
	s_add_u32 s0, s86, 0x1f800000
	s_addc_u32 s1, s87, 0
	v_writelane_b32 v233, s0, 36
	s_ashr_i32 s71, s70, 31
	s_mov_b64 s[42:43], s[70:71]
	v_writelane_b32 v233, s1, 37
	s_ashr_i32 s0, s41, 31
	v_writelane_b32 v233, s0, 38
	s_lshl_b32 s0, s42, 5
	v_readlane_b32 s13, v233, 5
	s_and_b32 s15, s0, 0x60
	s_lshl_b32 s0, s13, 8
	s_add_i32 s48, 0, 0x12000
	s_ashr_i32 s14, s70, 3
	s_add_i32 s49, s48, s0
	s_cmp_lt_u32 s74, 64
	s_cselect_b64 s[24:25], -1, 0
	s_cmp_gt_u32 s74, 63
	s_cselect_b64 s[26:27], -1, 0
	s_cmpk_gt_u32 s74, 0x7f
	s_cselect_b64 s[0:1], -1, 0
	v_writelane_b32 v233, s0, 39
	s_cmpk_gt_u32 s74, 0xbf
	s_mul_i32 s4, s13, 0x480
	v_writelane_b32 v233, s1, 40
	s_cselect_b64 s[0:1], -1, 0
	v_writelane_b32 v233, s0, 41
	s_cmpk_gt_u32 s74, 0xff
	v_mov_b32_e32 v3, 0
	v_writelane_b32 v233, s1, 42
	s_cselect_b64 s[0:1], -1, 0
	v_writelane_b32 v233, s0, 43
	s_cmpk_gt_u32 s74, 0x13f
	s_waitcnt vmcnt(0)
	v_perm_b32 v88, v47, v0, s73
	v_writelane_b32 v233, s1, 44
	s_cselect_b64 s[0:1], -1, 0
	v_writelane_b32 v233, s0, 45
	s_cmpk_gt_u32 s74, 0x17f
	v_mov_b32_e32 v77, 0x260
	v_writelane_b32 v233, s1, 46
	s_cselect_b64 s[0:1], -1, 0
	v_writelane_b32 v233, s0, 47
	s_cmpk_gt_u32 s74, 0x1bf
	s_movk_i32 s76, 0x90
	v_writelane_b32 v233, s1, 48
	s_cselect_b64 s[0:1], -1, 0
	v_writelane_b32 v233, s0, 49
	s_cmpk_gt_u32 s74, 0x1ff
	v_mov_b64_e32 v[20:21], 0x1000
	v_writelane_b32 v233, s1, 50
	s_cselect_b64 s[0:1], -1, 0
	s_lshl_b32 s88, s13, 4
	v_writelane_b32 v233, s0, 51
	s_add_i32 s53, s88, 0
	s_lshr_b32 s5, s74, 7
	s_bfe_u32 s6, s74, 0x10006
	v_writelane_b32 v233, s1, 52
	s_cmpk_lt_u32 s74, 0x100
	s_mov_b32 s1, 0x9000
	s_cselect_b32 s0, 0, 0x2400
	s_cselect_b32 s7, s1, 0x1ce00
	s_movk_i32 s1, 0x4800
	s_cselect_b32 s8, s1, 0x6c00
	s_add_i32 s54, s0, 0
	s_bitcmp0_b32 s74, 7
	s_cselect_b32 s0, s1, 0x6c00
	s_add_i32 s55, s0, 0
	s_lshl_b32 s9, s6, 1
	s_cmpk_lt_u32 s74, 0x80
	s_cselect_b64 s[28:29], -1, 0
	s_cmp_eq_u32 s5, 2
	s_mov_b32 s0, 0x17200
	s_cselect_b32 s12, s0, 0x19600
	s_cmp_eq_u32 s5, 1
	s_cselect_b64 s[20:21], -1, 0
	s_and_b64 s[0:1], s[20:21], exec
	s_cselect_b32 s0, 0x14e00, s12
	s_add_i32 s56, s0, 0
	s_lshl_b32 s57, s6, 5
	s_lshl_b32 s58, s6, 6
	s_and_b32 s0, 64, s74
	s_cmp_eq_u32 s6, 0
	s_cselect_b64 s[30:31], -1, 0
	s_cmp_lg_u32 s0, 0
	s_cselect_b64 s[34:35], -1, 0
	s_or_b32 s62, s9, 1
	s_lshl_b32 s60, s62, 4
	s_lshl_b32 s61, s62, 5
	s_cmp_lg_u32 s13, 1
	s_mul_i32 s0, s13, 0x300
	s_cselect_b64 s[36:37], -1, 0
	s_add_i32 s64, s0, 0
	s_sub_i32 s63, s88, 64
	s_add_i32 s64, s64, 0x1ba00
	s_lshl_b32 s65, s13, 5
	s_cmpk_lt_u32 s74, 0xc0
	v_writelane_b32 v233, s74, 53
	s_cselect_b64 s[38:39], -1, 0
	s_add_i32 s0, s88, 16
	v_writelane_b32 v233, s0, 54
	s_lshl_b32 s0, s6, 3
	s_add_i32 s71, s0, 0
	s_lshl_b32 s0, s42, 9
	s_and_b32 s0, s0, 0x800
	v_writelane_b32 v233, s14, 56
	s_add_i32 s0, s14, s0
	v_writelane_b32 v233, s15, 57
	s_add_i32 s75, s0, s15
	s_load_dwordx2 s[40:41], s[82:83], 0x58
	s_load_dwordx4 s[12:15], s[82:83], 0x88
	s_lshl_b32 s69, s63, 1
	s_add_i32 s70, s69, 0
	s_lshl_b32 s1, s5, 6
	v_cndmask_b32_e64 v69, 0, 1, s[20:21]
	s_mul_i32 s59, s6, 0xa00
	s_mulk_i32 s62, 0x500
	s_add_i32 s66, s7, 0
	s_add_i32 s67, s8, 0
	s_and_b32 s68, s88, 48
	s_add_i32 s70, s70, 0x1ce00
	s_add_i32 s71, s71, s1
	s_add_i32 s72, s48, s65
	s_add_i32 s74, s4, 0
	s_add_i32 s77, 0, 0xfc00
	v_mov_b32_e32 v78, 0xf800000
	v_mov_b32_e32 v79, 0x4f800000
	v_mov_b32_e32 v124, v3
	v_mov_b32_e32 v125, v3
	v_mov_b32_e32 v80, 0x1e800
	v_mov_b32_e32 v81, 0x14400
	v_mov_b32_e32 v82, 0x900
	v_mov_b32_e32 v83, 0x1200
	v_mov_b32_e32 v87, 0x1b00
	s_mov_b32 s78, 0
	v_writelane_b32 v233, s42, 58
	s_mov_b32 s16, 0
	s_nop 0
	v_writelane_b32 v233, s43, 59
	v_mov_b32_e32 v213, v23
	v_ashrrev_i32_e32 v214, 3, v213
	v_add_u32_e32 v215, s33, v214
	v_mul_lo_u32 v216, v215, s76
	v_lshlrev_b32_e32 v217, 4, v213
	v_and_b32_e32 v218, 0x70, v217
	v_add3_u32 v130, 0, v216, v218
	v_mov_b32_e32 v213, v23
	v_and_b32_e32 v214, 0xffffff0, v213
	v_mul_lo_u32 v215, v214, s76
	v_lshlrev_b32_e32 v216, 1, v213
	v_add3_u32 v131, 0, v215, v216
	v_mov_b32_e32 v213, v23
	v_and_b32_e32 v214, 15, v213
	v_or_b32_e32 v215, s63, v214
	v_mul_lo_u32 v216, v215, s76
	v_and_b32_e32 v217, -16, v213
	v_add3_u32 v132, 0, v216, v217
	s_add_i32 s90, 0, 0x14e00
	v_mov_b32_e32 v213, v23
	v_ashrrev_i32_e32 v214, 3, v213
	v_add_u32_e32 v215, s33, v214
	v_mul_lo_u32 v216, v215, s76
	v_lshlrev_b32_e32 v217, 4, v213
	v_and_b32_e32 v218, 0x70, v217
	v_add3_u32 v133, s90, v216, v218
	s_add_i32 s91, 0, 0x14e00
	v_mov_b32_e32 v213, v23
	v_and_b32_e32 v214, 15, v213
	v_mul_u32_u24_e32 v215, 0x90, v214
	v_and_b32_e32 v216, -16, v213
	v_add3_u32 v134, s91, v215, v216
	s_add_i32 s92, 0, 0x1ba00
	v_mov_b32_e32 v213, v23
	v_ashrrev_i32_e32 v214, 4, v213
	s_movk_i32 s93, 0x300
	v_mul_lo_u32 v215, v214, s93
	v_and_b32_e32 v216, 15, v213
	v_mul_u32_u24_e32 v217, 48, v216
	v_add3_u32 v135, s92, v215, v217
	s_add_i32 s94, 0, 0x1ce00
	v_mov_b32_e32 v213, v23
	v_ashrrev_i32_e32 v214, 3, v213
	v_add_u32_e32 v215, s33, v214
	v_mul_lo_u32 v216, v215, s76
	v_lshlrev_b32_e32 v217, 4, v213
	v_and_b32_e32 v218, 0x70, v217
	v_add3_u32 v136, s94, v216, v218
	s_add_i32 s95, 0, 0x1ce00
	v_mov_b32_e32 v213, v23
	v_and_b32_e32 v214, 15, v213
	v_or_b32_e32 v215, s63, v214
	v_mul_lo_u32 v216, v215, s76
	v_ashrrev_i32_e32 v217, 4, v213
	v_lshlrev_b32_e32 v218, 3, v217
	v_add3_u32 v138, s95, v216, v218
	v_mov_b32_e32 v213, v23
	v_ashrrev_i32_e32 v214, 3, v213
	v_add_u32_e32 v215, s33, v214
	v_mul_lo_u32 v216, v215, s76
	v_lshlrev_b32_e32 v217, 4, v213
	v_and_b32_e32 v218, 0x70, v217
	v_add3_u32 v139, s48, v216, v218
	v_mov_b32_e32 v213, v23
	v_and_b32_e32 v214, 15, v213
	v_or_b32_e32 v215, s57, v214
	v_mul_u32_u24_e32 v216, 0x90, v215
	v_and_b32_e32 v217, -16, v213
	v_add3_u32 v140, s54, v216, v217
	v_mov_b32_e32 v213, v23
	v_and_b32_e32 v214, 15, v213
	v_or_b32_e32 v215, s60, v214
	v_mul_u32_u24_e32 v216, 0x90, v215
	v_and_b32_e32 v217, -16, v213
	v_add3_u32 v141, s54, v216, v217
	v_mov_b32_e32 v213, v23
	v_and_b32_e32 v214, 15, v213
	v_mul_u32_u24_e32 v215, 0x90, v214
	v_add_u32_e32 v216, 0x1200, v215
	v_and_b32_e32 v217, -16, v213
	v_add3_u32 v142, s55, v216, v217
	v_mov_b32_e32 v213, v23
	v_and_b32_e32 v214, 15, v213
	v_mul_u32_u24_e32 v215, 0x90, v214
	v_add_u32_e32 v216, 0x900, v215
	v_and_b32_e32 v217, -16, v213
	v_add3_u32 v143, s55, v216, v217
	v_mov_b32_e32 v213, v23
	v_and_b32_e32 v214, 15, v213
	v_or_b32_e32 v215, 16, v214
	v_mul_u32_u24_e32 v216, 0x90, v215
	v_and_b32_e32 v217, -16, v213
	v_add3_u32 v144, s55, v216, v217
	v_mov_b32_e32 v213, v23
	v_and_b32_e32 v214, 15, v213
	v_or_b32_e32 v215, 32, v214
	v_mul_u32_u24_e32 v216, 0x90, v215
	v_and_b32_e32 v217, -16, v213
	v_add3_u32 v145, s55, v216, v217
	v_mov_b32_e32 v213, v23
	v_and_b32_e32 v214, 15, v213
	v_or_b32_e32 v215, 48, v214
	v_mul_u32_u24_e32 v216, 0x90, v215
	v_and_b32_e32 v217, -16, v213
	v_add3_u32 v146, s55, v216, v217
	v_mov_b32_e32 v213, v23
	v_mul_lo_u32 v214, v213, s76
	v_add_u32_e32 v147, 0, v214
	v_mov_b32_e32 v213, v23
	v_lshlrev_b32_e32 v214, 2, v213
	v_add_u32_e32 v215, 0, v214
	v_add_u32_e32 v148, 0x12000, v215
	v_mov_b32_e32 v213, v23
	v_and_b32_e32 v214, 15, v213
	v_mul_u32_u24_e32 v215, 0x50, v214
	v_and_b32_e32 v216, -16, v213
	v_add3_u32 v217, 0, v215, v216
	v_add_u32_e32 v218, s59, v217
	v_add_u32_e32 v149, 0x14400, v218
	v_mov_b32_e32 v213, v23
	v_and_b32_e32 v214, 15, v213
	v_mul_u32_u24_e32 v215, 0x50, v214
	v_and_b32_e32 v216, -16, v213
	v_add3_u32 v217, 0, v215, v216
	v_add_u32_e32 v218, s59, v217
	v_add_u32_e32 v150, 0x1e800, v218
	v_mov_b32_e32 v213, v23
	v_ashrrev_i32_e32 v214, 4, v213
	v_lshlrev_b32_e32 v215, 3, v214
	v_add_u32_e32 v216, s56, v215
	v_and_b32_e32 v217, 15, v213
	v_or_b32_e32 v218, s57, v217
	v_mul_u32_u24_e32 v219, 0x90, v218
	v_add_u32_e32 v151, v216, v219
	v_mov_b32_e32 v213, v23
	v_ashrrev_i32_e32 v214, 4, v213
	v_lshlrev_b32_e32 v215, 3, v214
	v_add_u32_e32 v216, s56, v215
	v_and_b32_e32 v217, 15, v213
	v_or_b32_e32 v218, s60, v217
	v_mul_u32_u24_e32 v219, 0x90, v218
	v_add_u32_e32 v152, v216, v219
	v_mov_b32_e32 v213, v23
	v_ashrrev_i32_e32 v214, 4, v213
	v_lshlrev_b32_e32 v215, 3, v214
	v_add_u32_e32 v216, s48, v215
	v_add_u32_e32 v217, s58, v216
	v_and_b32_e32 v218, 15, v213
	v_mul_u32_u24_e32 v219, 0x90, v218
	v_add_u32_e32 v220, 0x1200, v219
	v_add_u32_e32 v153, v217, v220
	v_mov_b32_e32 v213, v23
	v_ashrrev_i32_e32 v214, 4, v213
	v_lshlrev_b32_e32 v215, 3, v214
	v_add_u32_e32 v216, s48, v215
	v_add_u32_e32 v217, s58, v216
	v_and_b32_e32 v218, 15, v213
	v_mul_u32_u24_e32 v219, 0x90, v218
	v_add_u32_e32 v220, 0x900, v219
	v_add_u32_e32 v154, v217, v220
	v_mov_b32_e32 v213, v23
	v_ashrrev_i32_e32 v214, 4, v213
	v_lshlrev_b32_e32 v215, 3, v214
	v_add_u32_e32 v216, s48, v215
	v_add_u32_e32 v217, s58, v216
	v_and_b32_e32 v218, 15, v213
	v_mul_u32_u24_e32 v219, 0x90, v218
	v_add_u32_e32 v155, v217, v219
	v_mov_b32_e32 v213, v23
	v_and_b32_e32 v214, 15, v213
	v_mov_b32_e32 v215, s55
	v_mad_u32_u24 v216, v214, s76, v215
	v_and_b32_e32 v217, -16, v213
	v_add_u32_e32 v156, v216, v217
	v_mov_b32_e32 v213, v23
	v_lshlrev_b32_e32 v214, 2, v213
	v_add_u32_e32 v158, s49, v214
	v_mov_b32_e32 v213, v23
	v_mul_lo_u32 v214, v213, s76
	v_add_u32_e32 v159, s53, v214
	v_mov_b32_e32 v213, v23
	v_and_b32_e32 v160, -16, v213
	v_mov_b32_e32 v213, v23
	v_and_b32_e32 v161, 15, v213
	v_mov_b32_e32 v213, v23
	v_ashrrev_i32_e32 v162, 4, v213
	v_mov_b32_e32 v213, v23
	v_ashrrev_i32_e32 v214, 4, v213
	v_lshlrev_b32_e32 v215, 2, v214
	v_add_u32_e32 v216, 16, v215
	v_and_b32_e32 v217, 15, v213
	v_or_b32_e32 v218, s60, v217
	v_cmp_le_i32_e32 vcc, v216, v218
	s_nop 1
	v_cndmask_b32_e64 v219, 0, 1, vcc
	v_cmp_lt_i32_e32 vcc, v216, v218
	s_nop 1
	v_cndmask_b32_e64 v220, 0, 1, vcc
	v_cndmask_b32_e64 v221, v219, v220, s[20:21]
	v_and_b32_e32 v222, 1, v221
	v_cmp_eq_u32_e32 vcc, 1, v222
	s_nop 1
	v_cndmask_b32_e64 v163, 0, -1, vcc
	v_mov_b32_e32 v213, v23
	v_ashrrev_i32_e32 v214, 4, v213
	v_lshlrev_b32_e32 v215, 2, v214
	v_add_u32_e32 v216, 17, v215
	v_and_b32_e32 v217, 15, v213
	v_or_b32_e32 v218, s60, v217
	v_cmp_le_i32_e32 vcc, v216, v218
	s_nop 1
	v_cndmask_b32_e64 v219, 0, 1, vcc
	v_cmp_lt_i32_e32 vcc, v216, v218
	s_nop 1
	v_cndmask_b32_e64 v220, 0, 1, vcc
	v_cndmask_b32_e64 v221, v219, v220, s[20:21]
	v_and_b32_e32 v222, 1, v221
	v_cmp_eq_u32_e32 vcc, 1, v222
	s_nop 1
	v_cndmask_b32_e64 v164, 0, -1, vcc
	v_mov_b32_e32 v213, v23
	v_ashrrev_i32_e32 v214, 4, v213
	v_cmp_gt_i32_e32 vcc, 2, v214
	s_nop 1
	v_cndmask_b32_e64 v165, 0, -1, vcc
	v_mov_b32_e32 v213, v23
	v_and_b32_e32 v214, 15, v213
	v_or_b32_e32 v215, s57, v214
	v_ashrrev_i32_e32 v216, 4, v213
	v_lshlrev_b32_e32 v217, 2, v216
	v_or_b32_e32 v218, v217, v69
	v_cmp_gt_i32_e32 vcc, v215, v218
	s_nop 1
	v_cndmask_b32_e64 v166, 0, -1, vcc
	v_mov_b32_e32 v213, v23
	v_and_b32_e32 v214, 15, v213
	v_or_b32_e32 v215, s60, v214
	v_ashrrev_i32_e32 v216, 4, v213
	v_lshlrev_b32_e32 v217, 2, v216
	v_or_b32_e32 v218, v217, v69
	v_cmp_gt_i32_e32 vcc, v215, v218
	s_nop 1
	v_cndmask_b32_e64 v167, 0, -1, vcc
	v_mov_b32_e32 v213, v23
	v_and_b32_e32 v214, 15, v213
	v_ashrrev_i32_e32 v215, 4, v213
	v_lshlrev_b32_e32 v216, 2, v215
	v_add_u32_e32 v217, s57, v216
	v_cmp_le_i32_e32 vcc, v214, v217
	s_nop 1
	v_cndmask_b32_e64 v168, 0, -1, vcc
	v_mov_b32_e32 v213, v23
	v_and_b32_e32 v214, 15, v213
	v_or_b32_e32 v215, 16, v214
	v_ashrrev_i32_e32 v216, 4, v213
	v_lshlrev_b32_e32 v217, 2, v216
	v_add_u32_e32 v218, s57, v217
	v_cmp_le_i32_e32 vcc, v215, v218
	s_nop 1
	v_cndmask_b32_e64 v169, 0, -1, vcc
	v_mov_b32_e32 v213, v23
	v_and_b32_e32 v214, 15, v213
	v_or_b32_e32 v215, 32, v214
	v_ashrrev_i32_e32 v216, 4, v213
	v_lshlrev_b32_e32 v217, 2, v216
	v_add_u32_e32 v218, s57, v217
	v_cmp_le_i32_e32 vcc, v215, v218
	s_nop 1
	v_cndmask_b32_e64 v170, 0, -1, vcc
	v_mov_b32_e32 v213, v23
	v_and_b32_e32 v214, 15, v213
	v_add_u32_e32 v215, 13, v214
	v_ashrrev_i32_e32 v216, 4, v213
	v_lshlrev_b32_e32 v217, 2, v216
	v_add_u32_e32 v218, s57, v217
	v_cmp_lt_i32_e32 vcc, v215, v218
	s_nop 1
	v_cndmask_b32_e64 v171, 0, -1, vcc
	v_mov_b32_e32 v213, v23
	v_and_b32_e32 v214, 15, v213
	v_add_u32_e32 v215, 14, v214
	v_ashrrev_i32_e32 v216, 4, v213
	v_lshlrev_b32_e32 v217, 2, v216
	v_add_u32_e32 v218, s57, v217
	v_cmp_lt_i32_e32 vcc, v215, v218
	s_nop 1
	v_cndmask_b32_e64 v172, 0, -1, vcc
	v_mov_b32_e32 v213, v23
	v_ashrrev_i32_e32 v214, 4, v213
	v_lshlrev_b32_e32 v215, 2, v214
	v_add_u32_e32 v216, 16, v215
	v_cndmask_b32_e64 v217, 1, 0, s[20:21]
	v_and_b32_e32 v218, 15, v213
	v_or_b32_e32 v219, s57, v218
	v_add_u32_e32 v220, v217, v219
	v_cmp_lt_i32_e32 vcc, v216, v220
	s_nop 1
	v_cndmask_b32_e64 v173, 0, -1, vcc
	v_mov_b32_e32 v213, v23
	v_ashrrev_i32_e32 v214, 4, v213
	v_lshlrev_b32_e32 v215, 2, v214
	v_add_u32_e32 v216, 17, v215
	v_cndmask_b32_e64 v217, 1, 0, s[20:21]
	v_and_b32_e32 v218, 15, v213
	v_or_b32_e32 v219, s57, v218
	v_add_u32_e32 v220, v217, v219
	v_cmp_lt_i32_e32 vcc, v216, v220
	s_nop 1
	v_cndmask_b32_e64 v174, 0, -1, vcc
	v_mov_b32_e32 v213, v23
	v_ashrrev_i32_e32 v214, 4, v213
	v_lshlrev_b32_e32 v215, 2, v214
	v_add_u32_e32 v216, 18, v215
	v_cndmask_b32_e64 v217, 1, 0, s[20:21]
	v_and_b32_e32 v218, 15, v213
	v_or_b32_e32 v219, s57, v218
	v_add_u32_e32 v220, v217, v219
	v_cmp_lt_i32_e32 vcc, v216, v220
	s_nop 1
	v_cndmask_b32_e64 v175, 0, -1, vcc
	v_mov_b32_e32 v213, v23
	v_ashrrev_i32_e32 v214, 4, v213
	v_lshlrev_b32_e32 v215, 2, v214
	v_add_u32_e32 v216, 18, v215
	v_cndmask_b32_e64 v217, 1, 0, s[20:21]
	v_and_b32_e32 v218, 15, v213
	v_or_b32_e32 v219, s60, v218
	v_add_u32_e32 v220, v217, v219
	v_cmp_lt_i32_e32 vcc, v216, v220
	s_nop 1
	v_cndmask_b32_e64 v176, 0, -1, vcc
	v_mov_b32_e32 v213, v23
	v_ashrrev_i32_e32 v214, 4, v213
	v_lshlrev_b32_e32 v215, 2, v214
	v_add_u32_e32 v216, 19, v215
	v_cndmask_b32_e64 v217, 1, 0, s[20:21]
	v_and_b32_e32 v218, 15, v213
	v_or_b32_e32 v219, s57, v218
	v_add_u32_e32 v220, v217, v219
	v_cmp_lt_i32_e32 vcc, v216, v220
	s_nop 1
	v_cndmask_b32_e64 v177, 0, -1, vcc
	v_mov_b32_e32 v213, v23
	v_ashrrev_i32_e32 v214, 4, v213
	v_lshlrev_b32_e32 v215, 2, v214
	v_add_u32_e32 v216, 19, v215
	v_cndmask_b32_e64 v217, 1, 0, s[20:21]
	v_and_b32_e32 v218, 15, v213
	v_or_b32_e32 v219, s60, v218
	v_add_u32_e32 v220, v217, v219
	v_cmp_lt_i32_e32 vcc, v216, v220
	s_nop 1
	v_cndmask_b32_e64 v178, 0, -1, vcc
	v_mov_b32_e32 v213, v23
	v_and_b32_e32 v214, 15, v213
	v_add_u32_e32 v215, 29, v214
	v_ashrrev_i32_e32 v216, 4, v213
	v_lshlrev_b32_e32 v217, 2, v216
	v_add_u32_e32 v218, s57, v217
	v_cmp_lt_i32_e32 vcc, v215, v218
	s_nop 1
	v_cndmask_b32_e64 v179, 0, -1, vcc
	v_mov_b32_e32 v213, v23
	v_and_b32_e32 v214, 15, v213
	v_add_u32_e32 v215, 30, v214
	v_ashrrev_i32_e32 v216, 4, v213
	v_lshlrev_b32_e32 v217, 2, v216
	v_add_u32_e32 v218, s57, v217
	v_cmp_lt_i32_e32 vcc, v215, v218
	s_nop 1
	v_cndmask_b32_e64 v180, 0, -1, vcc
	v_mov_b32_e32 v213, v23
	v_ashrrev_i32_e32 v214, 4, v213
	v_lshlrev_b32_e32 v215, 2, v214
	v_add_u32_e32 v216, 32, v215
	v_cndmask_b32_e64 v217, 1, 0, s[20:21]
	v_and_b32_e32 v218, 15, v213
	v_or_b32_e32 v219, s57, v218
	v_add_u32_e32 v220, v217, v219
	v_cmp_lt_i32_e32 vcc, v216, v220
	s_nop 1
	v_cndmask_b32_e64 v181, 0, -1, vcc
	v_mov_b32_e32 v213, v23
	v_ashrrev_i32_e32 v214, 4, v213
	v_lshlrev_b32_e32 v215, 2, v214
	v_add_u32_e32 v216, 32, v215
	v_cndmask_b32_e64 v217, 1, 0, s[20:21]
	v_and_b32_e32 v218, 15, v213
	v_or_b32_e32 v219, s60, v218
	v_add_u32_e32 v220, v217, v219
	v_cmp_lt_i32_e32 vcc, v216, v220
	s_nop 1
	v_cndmask_b32_e64 v182, 0, -1, vcc
	v_mov_b32_e32 v213, v23
	v_ashrrev_i32_e32 v214, 4, v213
	v_lshlrev_b32_e32 v215, 2, v214
	v_add_u32_e32 v216, 33, v215
	v_cndmask_b32_e64 v217, 1, 0, s[20:21]
	v_and_b32_e32 v218, 15, v213
	v_or_b32_e32 v219, s57, v218
	v_add_u32_e32 v220, v217, v219
	v_cmp_lt_i32_e32 vcc, v216, v220
	s_nop 1
	v_cndmask_b32_e64 v183, 0, -1, vcc
	v_mov_b32_e32 v213, v23
	v_ashrrev_i32_e32 v214, 4, v213
	v_lshlrev_b32_e32 v215, 2, v214
	v_add_u32_e32 v216, 33, v215
	v_cndmask_b32_e64 v217, 1, 0, s[20:21]
	v_and_b32_e32 v218, 15, v213
	v_or_b32_e32 v219, s60, v218
	v_add_u32_e32 v220, v217, v219
	v_cmp_lt_i32_e32 vcc, v216, v220
	s_nop 1
	v_cndmask_b32_e64 v184, 0, -1, vcc
	v_mov_b32_e32 v213, v23
	v_ashrrev_i32_e32 v214, 4, v213
	v_lshlrev_b32_e32 v215, 2, v214
	v_add_u32_e32 v216, 34, v215
	v_cndmask_b32_e64 v217, 1, 0, s[20:21]
	v_and_b32_e32 v218, 15, v213
	v_or_b32_e32 v219, s57, v218
	v_add_u32_e32 v220, v217, v219
	v_cmp_lt_i32_e32 vcc, v216, v220
	s_nop 1
	v_cndmask_b32_e64 v185, 0, -1, vcc
	v_mov_b32_e32 v213, v23
	v_ashrrev_i32_e32 v214, 4, v213
	v_lshlrev_b32_e32 v215, 2, v214
	v_add_u32_e32 v216, 34, v215
	v_cndmask_b32_e64 v217, 1, 0, s[20:21]
	v_and_b32_e32 v218, 15, v213
	v_or_b32_e32 v219, s60, v218
	v_add_u32_e32 v220, v217, v219
	v_cmp_lt_i32_e32 vcc, v216, v220
	s_nop 1
	v_cndmask_b32_e64 v186, 0, -1, vcc
	v_mov_b32_e32 v213, v23
	v_ashrrev_i32_e32 v214, 4, v213
	v_lshlrev_b32_e32 v215, 2, v214
	v_add_u32_e32 v216, 35, v215
	v_cndmask_b32_e64 v217, 1, 0, s[20:21]
	v_and_b32_e32 v218, 15, v213
	v_or_b32_e32 v219, s57, v218
	v_add_u32_e32 v220, v217, v219
	v_cmp_lt_i32_e32 vcc, v216, v220
	s_nop 1
	v_cndmask_b32_e64 v187, 0, -1, vcc
	v_mov_b32_e32 v213, v23
	v_ashrrev_i32_e32 v214, 4, v213
	v_lshlrev_b32_e32 v215, 2, v214
	v_add_u32_e32 v216, 35, v215
	v_cndmask_b32_e64 v217, 1, 0, s[20:21]
	v_and_b32_e32 v218, 15, v213
	v_or_b32_e32 v219, s60, v218
	v_add_u32_e32 v220, v217, v219
	v_cmp_lt_i32_e32 vcc, v216, v220
	s_nop 1
	v_cndmask_b32_e64 v188, 0, -1, vcc
	v_mov_b32_e32 v213, v23
	v_ashrrev_i32_e32 v214, 4, v213
	v_lshlrev_b32_e32 v215, 2, v214
	v_add_u32_e32 v216, 48, v215
	v_cndmask_b32_e64 v217, 1, 0, s[20:21]
	v_and_b32_e32 v218, 15, v213
	v_or_b32_e32 v219, s60, v218
	v_add_u32_e32 v220, v217, v219
	v_cmp_lt_i32_e32 vcc, v216, v220
	s_nop 1
	v_cndmask_b32_e64 v189, 0, -1, vcc
	v_mov_b32_e32 v213, v23
	v_ashrrev_i32_e32 v214, 4, v213
	v_lshlrev_b32_e32 v215, 2, v214
	v_add_u32_e32 v216, 49, v215
	v_cndmask_b32_e64 v217, 1, 0, s[20:21]
	v_and_b32_e32 v218, 15, v213
	v_or_b32_e32 v219, s60, v218
	v_add_u32_e32 v220, v217, v219
	v_cmp_lt_i32_e32 vcc, v216, v220
	s_nop 1
	v_cndmask_b32_e64 v190, 0, -1, vcc
	v_mov_b32_e32 v213, v23
	v_ashrrev_i32_e32 v214, 4, v213
	v_lshlrev_b32_e32 v215, 2, v214
	v_add_u32_e32 v216, 50, v215
	v_cndmask_b32_e64 v217, 1, 0, s[20:21]
	v_and_b32_e32 v218, 15, v213
	v_or_b32_e32 v219, s60, v218
	v_add_u32_e32 v220, v217, v219
	v_cmp_lt_i32_e32 vcc, v216, v220
	s_nop 1
	v_cndmask_b32_e64 v191, 0, -1, vcc
	v_mov_b32_e32 v213, v23
	v_ashrrev_i32_e32 v214, 4, v213
	v_lshlrev_b32_e32 v215, 2, v214
	v_add_u32_e32 v216, 51, v215
	v_cndmask_b32_e64 v217, 1, 0, s[20:21]
	v_and_b32_e32 v218, 15, v213
	v_or_b32_e32 v219, s60, v218
	v_add_u32_e32 v220, v217, v219
	v_cmp_lt_i32_e32 vcc, v216, v220
	s_nop 1
	v_cndmask_b32_e64 v192, 0, -1, vcc
	v_mov_b32_e32 v213, v23
	v_and_b32_e32 v214, 15, v213
	v_ashrrev_i32_e32 v215, 4, v213
	v_lshlrev_b32_e32 v216, 2, v215
	v_add_u32_e32 v217, s57, v216
	v_cmp_lt_i32_e32 vcc, v214, v217
	s_nop 1
	v_cndmask_b32_e64 v193, 0, -1, vcc
	v_mov_b32_e32 v213, v23
	v_and_b32_e32 v214, 15, v213
	v_ashrrev_i32_e32 v215, 4, v213
	v_lshlrev_b32_e32 v216, 2, v215
	v_add_u32_e32 v217, s57, v216
	v_or_b32_e32 v218, 2, v217
	v_cmp_lt_i32_e32 vcc, v214, v218
	s_nop 1
	v_cndmask_b32_e64 v194, 0, -1, vcc
	v_mov_b32_e32 v213, v23
	v_and_b32_e32 v214, 15, v213
	v_ashrrev_i32_e32 v215, 4, v213
	v_lshlrev_b32_e32 v216, 2, v215
	v_add_u32_e32 v217, s57, v216
	v_or_b32_e32 v218, 3, v217
	v_cmp_lt_i32_e32 vcc, v214, v218
	s_nop 1
	v_cndmask_b32_e64 v195, 0, -1, vcc
	v_mov_b32_e32 v213, v23
	v_ashrrev_i32_e32 v214, 4, v213
	v_lshlrev_b32_e32 v215, 2, v214
	v_cndmask_b32_e64 v216, 1, 0, s[20:21]
	v_and_b32_e32 v217, 15, v213
	v_or_b32_e32 v218, s57, v217
	v_add_u32_e32 v219, v216, v218
	v_cmp_lt_i32_e32 vcc, v215, v219
	s_nop 1
	v_cndmask_b32_e64 v196, 0, -1, vcc
	v_mov_b32_e32 v213, v23
	v_ashrrev_i32_e32 v214, 4, v213
	v_lshlrev_b32_e32 v215, 2, v214
	v_cndmask_b32_e64 v216, 1, 0, s[20:21]
	v_and_b32_e32 v217, 15, v213
	v_or_b32_e32 v218, s60, v217
	v_add_u32_e32 v219, v216, v218
	v_cmp_lt_i32_e32 vcc, v215, v219
	s_nop 1
	v_cndmask_b32_e64 v197, 0, -1, vcc
	v_mov_b32_e32 v213, v23
	v_and_b32_e32 v214, 15, v213
	v_or_b32_e32 v215, 16, v214
	v_ashrrev_i32_e32 v216, 4, v213
	v_lshlrev_b32_e32 v217, 2, v216
	v_add_u32_e32 v218, s57, v217
	v_cmp_lt_i32_e32 vcc, v215, v218
	s_nop 1
	v_cndmask_b32_e64 v198, 0, -1, vcc
	v_mov_b32_e32 v213, v23
	v_ashrrev_i32_e32 v214, 4, v213
	v_lshlrev_b32_e32 v215, 2, v214
	v_or_b32_e32 v216, 2, v215
	v_cndmask_b32_e64 v217, 1, 0, s[20:21]
	v_and_b32_e32 v218, 15, v213
	v_or_b32_e32 v219, s57, v218
	v_add_u32_e32 v220, v217, v219
	v_cmp_lt_i32_e32 vcc, v216, v220
	s_nop 1
	v_cndmask_b32_e64 v199, 0, -1, vcc
	v_mov_b32_e32 v213, v23
	v_ashrrev_i32_e32 v214, 4, v213
	v_lshlrev_b32_e32 v215, 2, v214
	v_or_b32_e32 v216, 2, v215
	v_cndmask_b32_e64 v217, 1, 0, s[20:21]
	v_and_b32_e32 v218, 15, v213
	v_or_b32_e32 v219, s60, v218
	v_add_u32_e32 v220, v217, v219
	v_cmp_lt_i32_e32 vcc, v216, v220
	s_nop 1
	v_cndmask_b32_e64 v200, 0, -1, vcc
	v_mov_b32_e32 v213, v23
	v_and_b32_e32 v214, 15, v213
	v_or_b32_e32 v215, 32, v214
	v_ashrrev_i32_e32 v216, 4, v213
	v_lshlrev_b32_e32 v217, 2, v216
	v_add_u32_e32 v218, s57, v217
	v_cmp_lt_i32_e32 vcc, v215, v218
	s_nop 1
	v_cndmask_b32_e64 v201, 0, -1, vcc
	v_mov_b32_e32 v213, v23
	v_ashrrev_i32_e32 v214, 4, v213
	v_lshlrev_b32_e32 v215, 2, v214
	v_or_b32_e32 v216, 3, v215
	v_cndmask_b32_e64 v217, 1, 0, s[20:21]
	v_and_b32_e32 v218, 15, v213
	v_or_b32_e32 v219, s57, v218
	v_add_u32_e32 v220, v217, v219
	v_cmp_lt_i32_e32 vcc, v216, v220
	s_nop 1
	v_cndmask_b32_e64 v202, 0, -1, vcc
	v_mov_b32_e32 v213, v23
	v_ashrrev_i32_e32 v214, 4, v213
	v_lshlrev_b32_e32 v215, 2, v214
	v_or_b32_e32 v216, 3, v215
	v_cndmask_b32_e64 v217, 1, 0, s[20:21]
	v_and_b32_e32 v218, 15, v213
	v_or_b32_e32 v219, s60, v218
	v_add_u32_e32 v220, v217, v219
	v_cmp_lt_i32_e32 vcc, v216, v220
	s_nop 1
	v_cndmask_b32_e64 v203, 0, -1, vcc
	v_mov_b32_e32 v213, v23
	v_lshl_add_u32 v204, v213, 1, s74
	v_mov_b32_e32 v213, v23
	v_ashrrev_i32_e32 v214, 4, v213
	s_movk_i32 s96, 0x500
	v_mul_lo_u32 v215, v214, s96
	v_cmp_gt_i32_e32 vcc, 2, v214
	s_nop 1
	v_cndmask_b32_e32 v216, v80, v81, vcc
	v_add3_u32 v217, 0, v215, v216
	v_mov_b32_e32 v205, v217
	v_mov_b32_e32 v206, s16
	v_mov_b32_e32 v207, v23
	v_mov_b32_e32 v213, v23
	v_and_b32_e32 v214, 15, v213
	v_mul_u32_u24_e32 v208, 0x90, v214
	v_mov_b32_e32 v213, v23
	v_and_b32_e32 v214, 15, v213
	v_or_b32_e32 v209, 16, v214
	v_mov_b32_e32 v213, v23
	v_and_b32_e32 v214, 15, v213
	v_or_b32_e32 v210, 32, v214
	v_mov_b32_e32 v213, v23
	v_and_b32_e32 v214, 15, v213
	v_or_b32_e32 v211, 48, v214
	s_branch .LBB0_664
.LBB0_662:
	s_waitcnt lgkmcnt(0)
	s_barrier
	s_ashr_i32 s45, s44, 31
	v_ashrrev_i32_e32 v0, 3, v28
	v_add_u32_e32 v0, s33, v0
	v_lshlrev_b32_e32 v1, 4, v28
	v_and_b32_e32 v2, 0x70, v1
	s_lshl_b64 s[0:1], s[44:45], 13
	s_add_u32 s4, s10, s0
	v_lshlrev_b32_e32 v0, 7, v0
	ds_read_b128 v[4:7], v130 offset:36864
	s_addc_u32 s5, s11, s1
	v_ashrrev_i32_e32 v1, 31, v0
	v_lshl_add_u64 v[8:9], s[4:5], 0, v[0:1]
	v_lshl_add_u64 v[12:13], v[8:9], 0, v[2:3]
	ds_read_b128 v[8:11], v139
	v_readlane_b32 s4, v233, 34
	v_readlane_b32 s5, v233, 35
	s_add_u32 s4, s4, s0
	s_addc_u32 s5, s5, s1
	s_waitcnt lgkmcnt(1)
	global_store_dwordx4 v[12:13], v[4:7], off
	s_waitcnt vmcnt(7)
	v_perm_b32 v88, v47, v88, s73
	v_lshl_add_u64 v[4:5], s[4:5], 0, v[0:1]
	v_lshl_add_u64 v[4:5], v[4:5], 0, v[2:3]
	s_add_i32 s4, 0, 0x14e00
	s_waitcnt lgkmcnt(0)
	global_store_dwordx4 v[4:5], v[8:11], off
	v_readlane_b32 s4, v233, 32
	s_add_u32 s4, s4, s0
	v_readlane_b32 s5, v233, 33
	s_addc_u32 s5, s5, s1
	ds_read_b128 v[4:7], v133
	v_lshl_add_u64 v[8:9], s[4:5], 0, v[0:1]
	s_add_i32 s4, 0, 0x1ce00
	v_lshl_add_u64 v[12:13], v[8:9], 0, v[2:3]
	ds_read_b128 v[8:11], v136
	s_add_u32 s0, s84, s0
	s_addc_u32 s1, s85, s1
	v_lshl_add_u64 v[0:1], s[0:1], 0, v[0:1]
	v_lshl_add_u64 v[0:1], v[0:1], 0, v[2:3]
	s_waitcnt lgkmcnt(1)
	global_store_dwordx4 v[12:13], v[4:7], off
	s_waitcnt lgkmcnt(0)
	global_store_dwordx4 v[0:1], v[8:11], off
	s_barrier
	s_load_dword s0, s[82:83], 0x110
	s_addk_i32 s75, 0x80
	s_waitcnt lgkmcnt(0)
	s_add_u32 s42, s42, s0
	v_readlane_b32 s0, v233, 38
	s_addc_u32 s43, s43, s0
	s_add_i32 s78, s78, 1
	s_mov_b64 s[0:1], 0

.LBB0_696:
	s_or_b64 exec, exec, s[4:5]
	v_lshlrev_b32_e32 v2, 16, v36
	v_add_f32_e32 v109, 0, v2
	v_lshlrev_b32_e32 v2, 16, v41
	v_add_f32_e32 v108, v109, v2
	v_lshlrev_b32_e32 v2, 16, v44
	v_add_f32_e32 v107, v108, v2
	v_lshlrev_b32_e32 v2, 16, v51
	v_add_f32_e32 v106, v107, v2
	v_lshlrev_b32_e32 v2, 16, v57
	v_add_f32_e32 v105, v106, v2
	v_lshlrev_b32_e32 v2, 16, v63
	v_add_f32_e32 v103, v105, v2
	v_lshlrev_b32_e32 v2, 16, v68
	v_add_f32_e32 v102, v103, v2
	v_lshlrev_b32_e32 v2, 16, v74
	v_add_f32_e32 v101, v102, v2
	ds_write_b32 v158, v101
	s_waitcnt lgkmcnt(0)
	s_barrier
	ds_read2st64_b32 v[34:35], v148 offset1:1
	ds_read2st64_b32 v[32:33], v148 offset0:2 offset1:3
	ds_read2st64_b32 v[30:31], v148 offset0:4 offset1:5
	ds_read2st64_b32 v[18:19], v148 offset0:6 offset1:7
	v_cndmask_b32_e64 v29, 0, 1, s[24:25]
	s_waitcnt lgkmcnt(3)
	v_add_f32_e32 v34, 0, v34
	v_add_f32_e32 v2, v34, v35
	s_waitcnt lgkmcnt(2)
	v_add_f32_e32 v2, v2, v32
	v_add_f32_e32 v2, v2, v33
	s_waitcnt lgkmcnt(1)
	v_add_f32_e32 v2, v2, v30
	v_add_f32_e32 v2, v2, v31
	s_waitcnt lgkmcnt(0)
	v_add_f32_e32 v2, v2, v18
	v_add_f32_e32 v2, v2, v19
	v_mul_f32_e32 v2, 0x3fb8aa3b, v2
	v_exp_f32_e32 v2, v2
	v_cmp_ne_u32_e64 s[22:23], 1, v29
	s_andn2_b64 vcc, exec, s[24:25]
	s_cbranch_vccnz .LBB0_698
	s_ashr_i32 s45, s44, 31
	s_lshl_b64 s[0:1], s[44:45], 8
	s_add_u32 s0, s50, s0
	s_addc_u32 s1, s51, s1
	v_ashrrev_i32_e32 v29, 31, v28
	v_lshl_add_u64 v[114:115], v[28:29], 2, s[0:1]
	global_store_dword v[114:115], v2, off
.LBB0_698:
	v_cndmask_b32_e64 v29, v34, 0, s[24:25]
	v_readlane_b32 s80, v233, 39
	v_add_f32_e32 v34, v35, v29
	v_readlane_b32 s81, v233, 40
	v_readlane_b32 s0, v233, 41
	v_readlane_b32 s1, v233, 42
	v_cndmask_b32_e64 v29, v29, v34, s[80:81]
	v_add_f32_e32 v32, v32, v29
	v_cndmask_b32_e64 v29, v29, v32, s[0:1]
	v_readlane_b32 s0, v233, 43
	v_add_f32_e32 v32, v33, v29
	v_readlane_b32 s1, v233, 44
	s_nop 1
	v_cndmask_b32_e64 v29, v29, v32, s[0:1]
	v_readlane_b32 s0, v233, 45
	v_add_f32_e32 v30, v30, v29
	v_readlane_b32 s1, v233, 46
	s_nop 0
	s_nop 0
	v_cndmask_b32_e64 v29, v29, v30, s[0:1]
	v_readlane_b32 s0, v233, 47
	v_add_f32_e32 v31, v31, v29
	v_readlane_b32 s1, v233, 48
	s_nop 1
	v_cndmask_b32_e64 v29, v29, v31, s[0:1]
	v_add_f32_e32 v18, v18, v29
	s_nop 1
	s_nop 0
	v_readlane_b32 s0, v233, 49
	v_readlane_b32 s1, v233, 50
	s_nop 1
	v_cndmask_b32_e64 v18, v29, v18, s[0:1]
	v_readlane_b32 s0, v233, 51
	v_add_f32_e32 v19, v19, v18
	v_readlane_b32 s1, v233, 52
	s_nop 1
	v_cndmask_b32_e64 v18, v18, v19, s[0:1]
	v_sqrt_f32_e32 v19, s46
	s_nop 0
	v_max_f32_e32 v19, 0x2b8cbccc, v19
	v_rcp_f32_e32 v19, v19
	s_nop 0
	v_mul_f32_e32 v19, v112, v19
	v_add_f32_e32 v109, v109, v18
	v_mul_f32_e32 v17, v19, v17
	v_sqrt_f32_e32 v29, s19
	s_nop 0
	v_max_f32_e32 v29, 0x2b8cbccc, v29
	v_rcp_f32_e32 v29, v29
	s_nop 0
	v_mul_f32_e32 v29, v111, v29
	v_mul_f32_e32 v15, v29, v15
	s_nop 0
	v_sqrt_f32_e32 v30, s18
	s_nop 0
	v_max_f32_e32 v30, 0x2b8cbccc, v30
	v_rcp_f32_e32 v30, v30
	s_nop 0
	v_mul_f32_e32 v114, v110, v30
	v_mul_f32_e32 v16, v114, v16
	s_nop 0
	v_sqrt_f32_e32 v30, s17
	s_nop 0
	v_max_f32_e32 v30, 0x2b8cbccc, v30
	v_rcp_f32_e32 v30, v30
	s_nop 0
	v_mul_f32_e32 v104, v104, v30
	v_mul_f32_e32 v14, v104, v14
	s_nop 0
	v_sqrt_f32_e32 v30, s9
	s_nop 0
	v_max_f32_e32 v30, 0x2b8cbccc, v30
	v_rcp_f32_e32 v30, v30
	s_nop 0
	v_mul_f32_e32 v100, v100, v30
	v_mul_f32_e32 v13, v100, v13
	s_nop 0
	v_sqrt_f32_e32 v30, s8
	s_nop 0
	v_max_f32_e32 v30, 0x2b8cbccc, v30
	v_rcp_f32_e32 v30, v30
	s_nop 0
	v_mul_f32_e32 v115, v99, v30
	v_lshlrev_b32_e32 v110, 16, v61
	v_mov_b32_e32 v111, s6
	v_mul_f32_e32 v11, v115, v11
	s_nop 0
	v_and_b32_e32 v31, 0xffff0000, v88
	v_sqrt_f32_e32 v30, s7
	s_nop 0
	v_max_f32_e32 v30, 0x2b8cbccc, v30
	v_rcp_f32_e32 v30, v30
	s_nop 0
	v_mul_f32_e32 v116, v98, v30
	v_lshlrev_b32_e32 v30, 16, v88
	v_lshlrev_b32_e32 v33, 16, v54
	v_lshlrev_b32_e32 v35, 16, v52
	v_lshlrev_b32_e32 v34, 16, v45
	v_mov_b32_e32 v32, v31
	v_pk_add_f32 v[30:31], v[30:31], v[34:35] neg_lo:[0,1] neg_hi:[0,1]
	v_pk_add_f32 v[98:99], v[34:35], v[32:33] neg_lo:[0,1] neg_hi:[0,1]
	v_pk_fma_f32 v[30:31], v[24:25], v[30:31], v[34:35] op_sel_hi:[0,1,1]
	v_pk_fma_f32 v[34:35], v[98:99], v[24:25], v[32:33] op_sel_hi:[1,0,1]
	v_mul_f32_e32 v32, s6, v79
	v_cmp_lt_f32_e32 vcc, s6, v78
	v_lshlrev_b32_e32 v99, 16, v66
	v_lshlrev_b32_e32 v98, 16, v56
	v_cndmask_b32_e32 v112, v111, v32, vcc
	v_sqrt_f32_e32 v113, v112
	v_lshlrev_b32_e32 v111, 16, v71
	v_pk_mov_b32 v[32:33], v[32:33], v[110:111] op_sel:[1,0]
	v_mul_f32_e32 v12, v116, v12
	v_add_u32_e32 v117, -1, v113
	v_fma_f32 v118, -v117, v113, v112
	v_cmp_ge_f32_e64 s[0:1], 0, v118
	v_add_u32_e32 v118, 1, v113
	v_pk_add_f32 v[32:33], v[32:33], v[98:99] neg_lo:[0,1] neg_hi:[0,1]
	v_cndmask_b32_e64 v117, v113, v117, s[0:1]
	v_fma_f32 v113, -v118, v113, v112
	v_cmp_lt_f32_e64 s[0:1], 0, v113
	v_pk_fma_f32 v[32:33], v[32:33], v[24:25], v[98:99] op_sel_hi:[1,0,1]
	s_nop 0
	v_cndmask_b32_e64 v113, v117, v118, s[0:1]
	v_mul_f32_e32 v117, 0x37800000, v113
	v_cndmask_b32_e32 v113, v113, v117, vcc
	v_cmp_class_f32_e32 vcc, v112, v77
	s_nop 1
	v_cndmask_b32_e32 v112, v113, v112, vcc
	v_max_f32_e32 v117, 0x2b8cbccc, v112
	v_div_scale_f32 v118, s[0:1], v117, v117, v97
	v_pk_add_f32 v[112:113], v[98:99], v[110:111] neg_lo:[0,1] neg_hi:[0,1]
	s_nop 0
	v_pk_fma_f32 v[98:99], v[112:113], v[24:25], v[110:111] op_sel_hi:[1,0,1]
	v_sqrt_f32_e32 v110, s6
	s_nop 0
	v_max_f32_e32 v110, 0x2b8cbccc, v110
	v_rcp_f32_e32 v110, v110
	s_nop 0
	v_mul_f32_e32 v97, v97, v110
	v_mul_f32_e32 v110, 0x3fb8aa3b, v18
	v_exp_f32_e32 v111, v110
	v_mul_f32_e32 v110, 0x3fb8aa3b, v109
	v_exp_f32_e32 v112, v110
	v_mul_f32_e32 v109, 0xbfb8aa3b, v109
	v_exp_f32_e32 v110, v109
	v_mul_f32_e32 v10, v97, v10
	v_mul_f32_e64 v97, v111, -v97
	v_mul_f32_e32 v96, v96, v112
	v_cvt_pk_bf16_f32 v109, v97, s0
	v_cvt_pk_bf16_f32 v96, v96, s0
	v_mul_f32_e32 v97, v10, v110
	v_mul_f32_e32 v111, v0, v110
	v_cvt_pk_bf16_f32 v113, v30, v31
	v_add_f32_e32 v31, v108, v18
	v_cvt_pk_bf16_f32 v97, v97, s0
	v_cvt_pk_bf16_f32 v111, v111, s0
	ds_write_b16 v204, v109
	ds_write_b16 v204, v96 offset:9216
	ds_write_b16 v204, v97 offset:18432
	ds_write_b16 v204, v111 offset:27648
	v_mul_f32_e32 v96, 0x3fb8aa3b, v31
	v_mul_f32_e32 v31, 0xbfb8aa3b, v31
	v_exp_f32_e32 v97, v96
	v_exp_f32_e32 v96, v31
	v_mul_f32_e64 v31, v112, -v116
	v_cvt_pk_bf16_f32 v112, v34, v35
	v_add_f32_e32 v34, v107, v18
	v_mul_f32_e32 v111, v4, v96
	v_mul_f32_e32 v35, 0x3fb8aa3b, v34
	v_cvt_pk_bf16_f32 v31, v31, s0
	v_mul_f32_e32 v94, v94, v97
	v_mul_f32_e32 v108, v12, v96
	v_cvt_pk_bf16_f32 v111, v111, s0
	v_exp_f32_e32 v35, v35
	v_mul_f32_e32 v34, 0xbfb8aa3b, v34
	v_cvt_pk_bf16_f32 v94, v94, s0
	v_cvt_pk_bf16_f32 v108, v108, s0
	ds_write_b16 v204, v31 offset:144
	ds_write_b16 v204, v94 offset:9360
	ds_write_b16 v204, v108 offset:18576
	ds_write_b16 v204, v111 offset:27792
	v_exp_f32_e32 v111, v34
	v_mul_f32_e64 v34, v97, -v115
	v_cvt_pk_bf16_f32 v94, v34, s0
	v_mul_f32_e32 v34, v92, v35
	v_cvt_pk_bf16_f32 v34, v34, s0
	v_mul_f32_e32 v92, v11, v111
	v_mul_f32_e32 v97, v1, v111
	v_cvt_pk_bf16_f32 v92, v92, s0
	v_cvt_pk_bf16_f32 v97, v97, s0
	ds_write_b16 v204, v94 offset:288
	ds_write_b16 v204, v34 offset:9504
	ds_write_b16 v204, v92 offset:18720
	ds_write_b16 v204, v97 offset:27936
	v_add_f32_e32 v34, v106, v18
	v_mul_f32_e32 v92, 0x3fb8aa3b, v34
	v_exp_f32_e32 v92, v92
	v_mul_f32_e32 v34, 0xbfb8aa3b, v34
	v_exp_f32_e32 v97, v34
	v_mul_f32_e64 v34, v35, -v100
	v_cvt_pk_bf16_f32 v100, v34, s0
	v_mul_f32_e32 v34, v90, v92
	v_cvt_pk_bf16_f32 v34, v34, s0
	v_mul_f32_e32 v35, v13, v97
	v_mul_f32_e32 v90, v5, v97
	v_cvt_pk_bf16_f32 v35, v35, s0
	v_cvt_pk_bf16_f32 v90, v90, s0
	ds_write_b16 v204, v100 offset:432
	ds_write_b16 v204, v34 offset:9648
	ds_write_b16 v204, v35 offset:18864
	ds_write_b16 v204, v90 offset:28080
	v_add_f32_e32 v34, v105, v18
	v_mul_f32_e32 v35, 0x3fb8aa3b, v34
	v_exp_f32_e32 v35, v35
	v_mul_f32_e32 v34, 0xbfb8aa3b, v34
	v_exp_f32_e32 v34, v34
	v_mul_f32_e64 v90, v92, -v104
	v_cvt_pk_bf16_f32 v105, v32, v33
	v_add_f32_e32 v32, v103, v18
	v_cvt_pk_bf16_f32 v92, v90, s0
	v_mul_f32_e32 v90, v95, v35
	v_mul_f32_e32 v33, 0x3fb8aa3b, v32
	v_cvt_pk_bf16_f32 v90, v90, s0
	v_mul_f32_e32 v95, v14, v34
	v_mul_f32_e32 v104, v6, v34
	v_exp_f32_e32 v33, v33
	v_mul_f32_e32 v32, 0xbfb8aa3b, v32
	v_cvt_pk_bf16_f32 v95, v95, s0
	v_cvt_pk_bf16_f32 v104, v104, s0
	ds_write_b16 v204, v92 offset:576
	ds_write_b16 v204, v90 offset:9792
	ds_write_b16 v204, v95 offset:19008
	ds_write_b16 v204, v104 offset:28224
	v_exp_f32_e32 v90, v32
	v_mul_f32_e64 v32, v35, -v114
	v_mul_f32_e32 v35, v93, v33
	v_cvt_pk_bf16_f32 v32, v32, s0
	v_cvt_pk_bf16_f32 v35, v35, s0
	v_mul_f32_e32 v93, v16, v90
	v_mul_f32_e32 v95, v8, v90
	v_cvt_pk_bf16_f32 v93, v93, s0
	v_cvt_pk_bf16_f32 v95, v95, s0
	ds_write_b16 v204, v32 offset:720
	ds_write_b16 v204, v35 offset:9936
	ds_write_b16 v204, v93 offset:19152
	ds_write_b16 v204, v95 offset:28368
	v_add_f32_e32 v35, v102, v18
	v_mul_f32_e32 v93, 0x3fb8aa3b, v35
	v_exp_f32_e32 v93, v93
	v_mul_f32_e32 v35, 0xbfb8aa3b, v35
	v_exp_f32_e32 v35, v35
	v_mul_f32_e64 v29, v33, -v29
	v_mul_f32_e32 v33, v91, v93
	v_cvt_pk_bf16_f32 v29, v29, s0
	v_cvt_pk_bf16_f32 v33, v33, s0
	v_mul_f32_e32 v91, v15, v35
	v_mul_f32_e32 v95, v7, v35
	v_add_f32_e32 v18, v101, v18
	v_cvt_pk_bf16_f32 v91, v91, s0
	v_cvt_pk_bf16_f32 v95, v95, s0
	ds_write_b16 v204, v29 offset:864
	ds_write_b16 v204, v33 offset:10080
	ds_write_b16 v204, v91 offset:19296
	ds_write_b16 v204, v95 offset:28512
	v_mul_f32_e32 v33, 0x3fb8aa3b, v18
	v_exp_f32_e32 v33, v33
	v_mul_f32_e32 v18, 0xbfb8aa3b, v18
	v_exp_f32_e32 v91, v18
	v_mul_f32_e64 v18, v93, -v19
	v_mul_f32_e32 v19, v89, v33
	v_cvt_pk_bf16_f32 v18, v18, s0
	v_cvt_pk_bf16_f32 v19, v19, s0
	v_mul_f32_e32 v33, v17, v91
	v_mul_f32_e32 v89, v9, v91
	v_cvt_pk_bf16_f32 v33, v33, s0
	v_cvt_pk_bf16_f32 v89, v89, s0
	ds_write_b16 v204, v18 offset:1008
	ds_write_b16 v204, v19 offset:10224
	ds_write_b16 v204, v33 offset:19440
	ds_write_b16 v204, v89 offset:28656
	v_lshlrev_b32_e32 v19, 16, v31
	v_or_b32_sdwa v30, v19, v109 dst_sel:DWORD dst_unused:UNUSED_PAD src0_sel:DWORD src1_sel:WORD_0
	v_lshlrev_b32_e32 v19, 16, v100
	v_lshlrev_b32_e32 v18, 16, v18
	v_or_b32_sdwa v31, v19, v94 dst_sel:DWORD dst_unused:UNUSED_PAD src0_sel:DWORD src1_sel:WORD_0
	v_lshlrev_b32_e32 v19, 16, v32
	v_or_b32_sdwa v33, v18, v29 dst_sel:DWORD dst_unused:UNUSED_PAD src0_sel:DWORD src1_sel:WORD_0
	v_or_b32_sdwa v32, v19, v92 dst_sel:DWORD dst_unused:UNUSED_PAD src0_sel:DWORD src1_sel:WORD_0
	v_pk_mul_f32 v[18:19], v[2:3], v[110:111] op_sel_hi:[0,1]
	ds_write_b128 v159, v[30:33] offset:36864
	v_pk_mul_f32 v[30:31], v[2:3], v[96:97] op_sel_hi:[0,1]
	v_pk_mul_f32 v[10:11], v[10:11], v[18:19]
	v_pk_mul_f32 v[0:1], v[0:1], v[18:19]
	v_cvt_pk_bf16_f32 v32, v10, v11
	v_pk_mul_f32 v[10:11], v[12:13], v[30:31]
	v_cvt_pk_bf16_f32 v98, v98, v99
	v_cvt_pk_bf16_f32 v10, v10, v11
	v_and_b32_e32 v11, 0xffff0000, v10
	v_lshlrev_b32_e32 v10, 16, v10
	v_or_b32_sdwa v11, v11, v32 dst_sel:DWORD dst_unused:UNUSED_PAD src0_sel:DWORD src1_sel:WORD_1
	v_or_b32_sdwa v10, v10, v32 dst_sel:DWORD dst_unused:UNUSED_PAD src0_sel:DWORD src1_sel:WORD_0
	v_pk_mul_f32 v[32:33], v[2:3], v[34:35] op_sel_hi:[0,1]
	v_pk_mul_f32 v[34:35], v[2:3], v[90:91] op_sel_hi:[0,1]
	v_pk_mul_f32 v[12:13], v[14:15], v[32:33]
	s_mov_b64 s[0:1], -1
	v_cvt_pk_bf16_f32 v2, v12, v13
	v_pk_mul_f32 v[12:13], v[16:17], v[34:35]
	s_and_b64 vcc, exec, s[80:81]
	v_cvt_pk_bf16_f32 v12, v12, v13
	v_and_b32_e32 v13, 0xffff0000, v12
	v_lshlrev_b32_e32 v12, 16, v12
	v_or_b32_sdwa v13, v13, v2 dst_sel:DWORD dst_unused:UNUSED_PAD src0_sel:DWORD src1_sel:WORD_1
	v_or_b32_sdwa v12, v12, v2 dst_sel:DWORD dst_unused:UNUSED_PAD src0_sel:DWORD src1_sel:WORD_0
	v_cvt_pk_bf16_f32 v2, v0, v1
	v_pk_mul_f32 v[0:1], v[4:5], v[30:31]
	ds_write_b128 v159, v[10:13] offset:46080
	v_cvt_pk_bf16_f32 v0, v0, v1
	v_and_b32_e32 v1, 0xffff0000, v0
	v_lshlrev_b32_e32 v0, 16, v0
	v_or_b32_sdwa v5, v1, v2 dst_sel:DWORD dst_unused:UNUSED_PAD src0_sel:DWORD src1_sel:WORD_1
	v_or_b32_sdwa v4, v0, v2 dst_sel:DWORD dst_unused:UNUSED_PAD src0_sel:DWORD src1_sel:WORD_0
	v_pk_mul_f32 v[0:1], v[6:7], v[32:33]
	v_mov_b32_e32 v12, s55
	v_cvt_pk_bf16_f32 v2, v0, v1
	v_pk_mul_f32 v[0:1], v[8:9], v[34:35]
	s_nop 0
	v_cvt_pk_bf16_f32 v0, v0, v1
	v_and_b32_e32 v1, 0xffff0000, v0
	v_lshlrev_b32_e32 v0, 16, v0
	v_or_b32_sdwa v7, v1, v2 dst_sel:DWORD dst_unused:UNUSED_PAD src0_sel:DWORD src1_sel:WORD_1
	v_or_b32_sdwa v6, v0, v2 dst_sel:DWORD dst_unused:UNUSED_PAD src0_sel:DWORD src1_sel:WORD_0
	v_and_b32_e32 v0, 0xffff0000, v112
	v_lshlrev_b32_e32 v1, 16, v112
	ds_write_b128 v159, v[4:7] offset:55296
	v_or_b32_sdwa v5, v0, v113 dst_sel:DWORD dst_unused:UNUSED_PAD src0_sel:DWORD src1_sel:WORD_1
	v_or_b32_sdwa v4, v1, v113 dst_sel:DWORD dst_unused:UNUSED_PAD src0_sel:DWORD src1_sel:WORD_0
	v_and_b32_e32 v0, 0xffff0000, v98
	v_lshlrev_b32_e32 v1, 16, v98
	v_or_b32_sdwa v7, v0, v105 dst_sel:DWORD dst_unused:UNUSED_PAD src0_sel:DWORD src1_sel:WORD_1
	v_or_b32_sdwa v6, v1, v105 dst_sel:DWORD dst_unused:UNUSED_PAD src0_sel:DWORD src1_sel:WORD_0
	ds_write_b128 v159, v[4:7] offset:64512
	s_waitcnt lgkmcnt(0)
	s_barrier
	s_nop 0
	v_and_b32_e32 v0, 15, v28
	v_and_b32_e32 v1, -16, v28
	v_mad_u32_u24 v12, v0, s76, v12
	v_add_u32_e32 v30, v12, v1
	ds_read_b128 v[8:11], v140
	ds_read_b128 v[4:7], v140 offset:64
	ds_read_b128 v[16:19], v156
	ds_read_b128 v[12:15], v156 offset:64
	v_ashrrev_i32_e32 v2, 4, v28
	v_lshlrev_b32_e32 v29, 2, v2
	v_lshlrev_b32_e32 v2, 3, v2
	v_add_u32_e32 v33, s56, v2
	v_or_b32_e32 v89, v29, v69
	s_cbranch_vccz .LBB0_700
	s_waitcnt lgkmcnt(1)
	v_mfma_f32_16x16x32_bf16 v[94:97], v[16:19], v[8:11], 0
	s_mov_b64 s[0:1], 0
	s_waitcnt lgkmcnt(0)
	v_mfma_f32_16x16x32_bf16 v[94:97], v[12:15], v[4:7], v[94:97]
	s_nop 7
	v_bfi_b32 v35, v196, v94, v206
	v_and_b32_e32 v90, v166, v95
	v_cvt_pk_bf16_f32 v90, v35, v90
	v_and_b32_e32 v91, v199, v96
	v_and_b32_e32 v93, v202, v97
	v_cvt_pk_bf16_f32 v91, v91, v93
	ds_write_b64 v151, v[90:91]
.LBB0_700:
	v_add_u32_e32 v90, s48, v2
	v_mul_u32_u24_e32 v2, 0x50, v0
	v_mul_u32_u24_e32 v35, 0x90, v0
	v_cndmask_b32_e64 v95, 0, 1, s[30:31]
	v_add3_u32 v2, 0, v2, v1
	s_andn2_b64 vcc, exec, s[0:1]
	v_cmp_ne_u32_e64 s[8:9], 1, v95
	s_cbranch_vccnz .LBB0_703
	s_waitcnt lgkmcnt(1)
	v_mfma_f32_16x16x32_bf16 v[16:19], v[8:11], v[16:19], 0
	s_waitcnt lgkmcnt(0)
	v_mfma_f32_16x16x32_bf16 v[12:15], v[4:7], v[12:15], v[16:19]
	s_nop 7
	v_bfi_b32 v12, v193, v12, v206
	v_and_b32_e32 v13, v168, v13
	v_and_b32_e32 v14, v194, v14
	v_cvt_pk_bf16_f32 v16, v12, v13
	v_and_b32_e32 v15, v195, v15
	v_cvt_pk_bf16_f32 v17, v14, v15
	s_and_b64 vcc, exec, s[8:9]
	ds_write_b64 v155, v[16:17]
	s_cbranch_vccnz .LBB0_703
	ds_write_b128 v149, v[12:15]
.LBB0_703:
	v_readlane_b32 s0, v233, 39
	v_readlane_b32 s1, v233, 40
	s_mov_b64 s[6:7], -1
	s_andn2_b64 vcc, exec, s[0:1]
	s_waitcnt lgkmcnt(0)
	v_cndmask_b32_e64 v12, 0, 1, s[0:1]
	v_cmp_ne_u32_e64 s[4:5], 1, v12
	v_cndmask_b32_e64 v12, 0, 1, s[34:35]
	v_cmp_ne_u32_e64 s[0:1], 1, v12
	s_cbranch_vccnz .LBB0_711
	v_mov_b32_e32 v12, 0
	s_and_b64 vcc, exec, s[0:1]
	v_mov_b32_e32 v13, 0
	v_mov_b32_e32 v14, 0
	v_mov_b32_e32 v15, 0
	s_cbranch_vccnz .LBB0_706
	ds_read_b128 v[12:15], v156 offset:2304
	ds_read_b128 v[16:19], v156 offset:2368
	s_waitcnt lgkmcnt(1)
	v_mfma_f32_16x16x32_bf16 v[12:15], v[12:15], v[8:11], 0
	s_waitcnt lgkmcnt(0)
	v_mfma_f32_16x16x32_bf16 v[12:15], v[16:19], v[4:7], v[12:15]
.LBB0_706:
	s_nop 7
	v_and_b32_e32 v12, v173, v12
	v_and_b32_e32 v13, v174, v13
	v_cvt_pk_bf16_f32 v12, v12, v13
	v_and_b32_e32 v14, v175, v14
	v_and_b32_e32 v15, v177, v15
	v_cvt_pk_bf16_f32 v13, v14, v15
	ds_write_b64 v151, v[12:13] offset:32

.LBB0_708:
	v_mov_b32_e32 v12, 0
	s_and_b64 vcc, exec, s[0:1]
	v_mov_b32_e32 v13, 0
	v_mov_b32_e32 v14, 0
	v_mov_b32_e32 v15, 0
	s_cbranch_vccnz .LBB0_710
	ds_read_b128 v[12:15], v156 offset:4608
	ds_read_b128 v[16:19], v156 offset:4672
	s_waitcnt lgkmcnt(1)
	v_mfma_f32_16x16x32_bf16 v[12:15], v[12:15], v[8:11], 0
	s_waitcnt lgkmcnt(0)
	v_mfma_f32_16x16x32_bf16 v[12:15], v[16:19], v[4:7], v[12:15]
.LBB0_710:
	s_nop 7
	v_and_b32_e32 v12, v181, v12
	v_and_b32_e32 v13, v183, v13
	v_cvt_pk_bf16_f32 v12, v12, v13
	v_and_b32_e32 v14, v185, v14
	v_and_b32_e32 v15, v187, v15
	v_cvt_pk_bf16_f32 v13, v14, v15
	ds_write_b64 v151, v[12:13] offset:64
	s_branch .LBB0_720
.LBB0_711:
	s_and_b64 vcc, exec, s[6:7]
	s_cbranch_vccz .LBB0_707
	v_mov_b32_e32 v12, 0
	s_and_b64 vcc, exec, s[0:1]
	v_mov_b32_e32 v13, 0
	v_mov_b32_e32 v14, 0
	v_mov_b32_e32 v15, 0
	s_cbranch_vccnz .LBB0_714
	ds_read_b128 v[12:15], v143
	ds_read_b128 v[96:99], v143 offset:64
	s_waitcnt lgkmcnt(1)
	v_mfma_f32_16x16x32_bf16 v[12:15], v[8:11], v[12:15], 0
	s_waitcnt lgkmcnt(0)
	v_mfma_f32_16x16x32_bf16 v[12:15], v[4:7], v[96:99], v[12:15]
.LBB0_714:
	s_nop 7
	v_and_b32_e32 v12, v198, v12
	v_and_b32_e32 v13, v169, v13
	v_cvt_pk_bf16_f32 v12, v12, v13
	v_and_b32_e32 v14, v172, v14
	v_and_b32_e32 v15, v171, v15
	v_cvt_pk_bf16_f32 v13, v14, v15
	ds_write_b64 v154, v[12:13]
	s_and_b64 vcc, exec, s[4:5]
	s_mov_b64 s[6:7], -1
	s_cbranch_vccz .LBB0_708
.LBB0_715:
	s_and_b64 vcc, exec, s[6:7]
	s_cbranch_vccz .LBB0_720
	v_mov_b32_e32 v12, 0
	s_and_b64 vcc, exec, s[0:1]
	v_mov_b32_e32 v13, 0
	v_mov_b32_e32 v14, 0
	v_mov_b32_e32 v15, 0
	s_cbranch_vccnz .LBB0_718
	ds_read_b128 v[12:15], v142
	ds_read_b128 v[96:99], v142 offset:64
	s_waitcnt lgkmcnt(1)
	v_mfma_f32_16x16x32_bf16 v[8:11], v[8:11], v[12:15], 0
	s_waitcnt lgkmcnt(0)
	v_mfma_f32_16x16x32_bf16 v[12:15], v[4:7], v[96:99], v[8:11]
.LBB0_718:
	s_nop 7
	v_and_b32_e32 v4, v201, v12
	v_and_b32_e32 v5, v170, v13
	v_cvt_pk_bf16_f32 v8, v4, v5
	v_and_b32_e32 v6, v180, v14
	v_and_b32_e32 v7, v179, v15
	v_cvt_pk_bf16_f32 v9, v6, v7
	s_and_b64 vcc, exec, s[0:1]
	ds_write_b64 v153, v[8:9]
	s_cbranch_vccnz .LBB0_720
	ds_write_b128 v150, v[4:7]
.LBB0_720:
	s_and_b64 vcc, exec, s[4:5]
	s_mov_b64 s[6:7], -1
	s_cbranch_vccnz .LBB0_722
	s_mov_b64 s[6:7], 0
	ds_write_b64 v151, v[124:125] offset:96
.LBB0_722:
	s_andn2_b64 vcc, exec, s[6:7]
	s_cbranch_vccnz .LBB0_724
	ds_write_b64 v155, v[124:125] offset:6912
.LBB0_724:
	v_or_b32_e32 v34, s60, v0
	v_mul_u32_u24_e32 v91, 0x90, v34
	ds_read_b128 v[8:11], v141
	ds_read_b128 v[4:7], v141 offset:64
	ds_read_b128 v[16:19], v156
	ds_read_b128 v[12:15], v156 offset:64
	s_mov_b64 s[6:7], -1
	s_and_b64 vcc, exec, s[4:5]
	v_add_u32_e32 v33, v33, v91
	s_cbranch_vccnz .LBB0_728
	s_waitcnt lgkmcnt(1)
	v_mfma_f32_16x16x32_bf16 v[92:95], v[16:19], v[8:11], 0
	s_waitcnt lgkmcnt(0)
	v_mfma_f32_16x16x32_bf16 v[92:95], v[12:15], v[4:7], v[92:95]
	s_nop 7
	v_bfi_b32 v91, v197, v92, v206
	v_and_b32_e32 v89, v167, v93
	v_and_b32_e32 v32, v200, v94
	v_cvt_pk_bf16_f32 v92, v91, v89
	v_and_b32_e32 v31, v203, v95
	v_cvt_pk_bf16_f32 v93, v32, v31
	ds_write_b64 v152, v[92:93]
	v_add_u32_e32 v32, s60, v29
	v_add_u32_e32 v31, s61, v90
	s_cbranch_execz .LBB0_729

.LBB0_727:
	s_waitcnt lgkmcnt(0)
	ds_read_b128 v[12:15], v156 offset:2304
	ds_read_b128 v[16:19], v156 offset:2368
	v_add_u32_e32 v35, 16, v29
	v_cmp_lt_i32_e32 vcc, v35, v34
	s_waitcnt lgkmcnt(1)
	v_mfma_f32_16x16x32_bf16 v[12:15], v[12:15], v[8:11], 0
	v_cndmask_b32_e64 v89, 0, 1, vcc
	v_cmp_le_i32_e32 vcc, v35, v34
	s_waitcnt lgkmcnt(0)
	v_mfma_f32_16x16x32_bf16 v[12:15], v[16:19], v[4:7], v[12:15]
	v_cndmask_b32_e64 v35, 0, 1, vcc
	v_cndmask_b32_e64 v35, v35, v89, s[20:21]
	v_add_u32_e32 v89, 17, v29
	v_and_b32_e32 v35, 1, v35
	s_nop 1
	s_nop 1
	v_bfi_b32 v12, v163, v12, v206
	s_nop 1
	v_and_b32_e32 v13, v164, v13
	v_cvt_pk_bf16_f32 v12, v12, v13
	v_add_u32_e32 v16, 19, v29
	v_and_b32_e32 v14, v176, v14
	v_and_b32_e32 v15, v178, v15
	v_cvt_pk_bf16_f32 v13, v14, v15
	ds_write_b64 v152, v[12:13] offset:32
	s_cbranch_execnz .LBB0_733
	s_branch .LBB0_731

.LBB0_729:
	s_waitcnt lgkmcnt(1)
	v_mfma_f32_16x16x32_bf16 v[16:19], v[8:11], v[16:19], 0
	v_cmp_lt_i32_e32 vcc, v161, v32
	v_or_b32_e32 v89, 2, v32
	s_waitcnt lgkmcnt(0)
	v_mfma_f32_16x16x32_bf16 v[12:15], v[4:7], v[12:15], v[16:19]
	s_nop 2
	s_nop 0
	v_or_b32_e32 v16, 3, v32
	s_nop 3
	v_cndmask_b32_e32 v12, v206, v12, vcc
	v_cmp_le_i32_e32 vcc, v161, v32
	s_nop 1
	v_cndmask_b32_e32 v13, 0, v13, vcc
	v_cmp_lt_i32_e32 vcc, v161, v89
	v_cvt_pk_bf16_f32 v12, v12, v13
	s_nop 0
	v_cndmask_b32_e32 v14, 0, v14, vcc
	v_cmp_lt_i32_e32 vcc, v161, v16
	s_nop 1
	v_cndmask_b32_e32 v15, 0, v15, vcc
	v_cvt_pk_bf16_f32 v13, v14, v15
	v_add_u32_e32 v14, v31, v208
	ds_write_b64 v14, v[12:13]
	s_and_b64 vcc, exec, s[4:5]
	s_mov_b64 s[6:7], -1
	s_cbranch_vccz .LBB0_727

.LBB0_731:
	v_or_b32_e32 v35, 16, v0
	s_waitcnt lgkmcnt(0)
	ds_read_b128 v[12:15], v144
	ds_read_b128 v[16:19], v144 offset:64
	v_cmp_lt_i32_e32 vcc, v209, v32
	v_add_u32_e32 v89, 14, v0
	s_waitcnt lgkmcnt(1)
	v_mfma_f32_16x16x32_bf16 v[12:15], v[8:11], v[12:15], 0
	v_add_u32_e32 v91, 13, v0
	s_waitcnt lgkmcnt(0)
	v_mfma_f32_16x16x32_bf16 v[12:15], v[4:7], v[16:19], v[12:15]
	v_mad_u32_u24 v18, v209, s76, v31
	s_nop 6
	v_cndmask_b32_e32 v12, v206, v12, vcc
	v_cmp_le_i32_e32 vcc, v209, v32
	s_nop 1
	v_cndmask_b32_e32 v13, 0, v13, vcc
	v_cmp_lt_i32_e32 vcc, v89, v32
	v_cvt_pk_bf16_f32 v16, v12, v13
	s_nop 0
	v_cndmask_b32_e32 v14, 0, v14, vcc
	v_cmp_lt_i32_e32 vcc, v91, v32
	s_nop 1
	v_cndmask_b32_e32 v15, 0, v15, vcc
	v_cvt_pk_bf16_f32 v17, v14, v15
	s_and_b64 vcc, exec, s[8:9]
	ds_write_b64 v18, v[16:17]
	s_cbranch_vccnz .LBB0_733
	v_add_u32_e32 v16, s62, v2
	v_add_u32_e32 v16, 0x14400, v16
	ds_write_b128 v16, v[12:15]
.LBB0_733:
	s_and_b64 vcc, exec, s[4:5]
	s_mov_b64 s[6:7], -1
	s_cbranch_vccnz .LBB0_741
	s_waitcnt lgkmcnt(0)
	v_mov_b32_e32 v12, 0
	s_and_b64 vcc, exec, s[0:1]
	v_mov_b32_e32 v13, 0
	v_mov_b32_e32 v14, 0
	v_mov_b32_e32 v15, 0
	s_cbranch_vccnz .LBB0_736
	ds_read_b128 v[12:15], v156 offset:4608
	ds_read_b128 v[16:19], v156 offset:4672
	s_waitcnt lgkmcnt(1)
	v_mfma_f32_16x16x32_bf16 v[12:15], v[12:15], v[8:11], 0
	s_waitcnt lgkmcnt(0)
	v_mfma_f32_16x16x32_bf16 v[12:15], v[16:19], v[4:7], v[12:15]
.LBB0_736:
	s_nop 7
	v_and_b32_e32 v12, v182, v12
	v_and_b32_e32 v13, v184, v13
	v_cvt_pk_bf16_f32 v12, v12, v13
	v_add_u32_e32 v16, 35, v29
	v_and_b32_e32 v14, v186, v14
	v_and_b32_e32 v15, v188, v15
	v_cvt_pk_bf16_f32 v13, v14, v15
	ds_write_b64 v152, v[12:13] offset:64

.LBB0_738:
	s_waitcnt lgkmcnt(0)
	v_mov_b32_e32 v12, 0
	s_and_b64 vcc, exec, s[0:1]
	v_mov_b32_e32 v13, 0
	v_mov_b32_e32 v14, 0
	v_mov_b32_e32 v15, 0
	s_cbranch_vccnz .LBB0_740
	ds_read_b128 v[12:15], v156 offset:6912
	ds_read_b128 v[16:19], v156 offset:6976
	s_waitcnt lgkmcnt(1)
	v_mfma_f32_16x16x32_bf16 v[12:15], v[12:15], v[8:11], 0
	s_waitcnt lgkmcnt(0)
	v_mfma_f32_16x16x32_bf16 v[12:15], v[16:19], v[4:7], v[12:15]
.LBB0_740:
	s_nop 7
	v_and_b32_e32 v12, v189, v12
	v_and_b32_e32 v13, v190, v13
	v_cvt_pk_bf16_f32 v12, v12, v13
	v_add_u32_e32 v16, 51, v29
	v_and_b32_e32 v14, v191, v14
	v_and_b32_e32 v15, v192, v15
	v_cvt_pk_bf16_f32 v13, v14, v15
	ds_write_b64 v152, v[12:13] offset:96
	s_branch .LBB0_750
.LBB0_741:
	s_and_b64 vcc, exec, s[6:7]
	s_cbranch_vccz .LBB0_737
	s_waitcnt lgkmcnt(1)
	v_or_b32_e32 v17, 32, v0
	v_mul_u32_u24_e32 v16, 0x90, v17
	s_waitcnt lgkmcnt(0)
	v_mov_b32_e32 v12, 0
	s_and_b64 vcc, exec, s[0:1]
	v_mov_b32_e32 v13, 0
	v_mov_b32_e32 v14, 0
	v_mov_b32_e32 v15, 0
	s_cbranch_vccnz .LBB0_744
	v_add3_u32 v18, s55, v16, v1
	ds_read_b128 v[12:15], v145
	ds_read_b128 v[90:93], v145 offset:64
	s_waitcnt lgkmcnt(1)
	v_mfma_f32_16x16x32_bf16 v[12:15], v[8:11], v[12:15], 0
	s_waitcnt lgkmcnt(0)
	v_mfma_f32_16x16x32_bf16 v[12:15], v[4:7], v[90:93], v[12:15]
.LBB0_744:
	v_cmp_lt_i32_e32 vcc, v210, v32
	s_nop 6
	v_cndmask_b32_e32 v12, 0, v12, vcc
	v_cmp_le_i32_e32 vcc, v210, v32
	v_add_u32_e32 v17, 30, v0
	s_nop 0
	v_cndmask_b32_e32 v13, 0, v13, vcc
	v_cmp_lt_i32_e32 vcc, v17, v32
	v_add_u32_e32 v17, 29, v0
	v_cvt_pk_bf16_f32 v12, v12, v13
	v_cndmask_b32_e32 v14, 0, v14, vcc
	v_cmp_lt_i32_e32 vcc, v17, v32
	s_nop 1
	v_cndmask_b32_e32 v15, 0, v15, vcc
	v_cvt_pk_bf16_f32 v13, v14, v15
	v_add_u32_e32 v14, v31, v16
	ds_write_b64 v14, v[12:13]
	s_and_b64 vcc, exec, s[4:5]
	s_mov_b64 s[4:5], -1
	s_cbranch_vccz .LBB0_738
.LBB0_745:
	s_and_b64 vcc, exec, s[4:5]
	s_cbranch_vccz .LBB0_750
	s_waitcnt lgkmcnt(1)
	v_or_b32_e32 v17, 48, v0
	v_mul_u32_u24_e32 v16, 0x90, v17
	s_waitcnt lgkmcnt(0)
	v_mov_b32_e32 v12, 0
	s_and_b64 vcc, exec, s[0:1]
	v_mov_b32_e32 v13, 0
	v_mov_b32_e32 v14, 0
	v_mov_b32_e32 v15, 0
	s_cbranch_vccnz .LBB0_748
	ds_read_b128 v[12:15], v146
	ds_read_b128 v[90:93], v146 offset:64
	s_waitcnt lgkmcnt(1)
	v_mfma_f32_16x16x32_bf16 v[8:11], v[8:11], v[12:15], 0
	s_waitcnt lgkmcnt(0)
	v_mfma_f32_16x16x32_bf16 v[12:15], v[4:7], v[90:93], v[8:11]
.LBB0_748:
	v_cmp_lt_i32_e32 vcc, v211, v32
	v_add_u32_e32 v1, 46, v0
	v_add_u32_e32 v0, 45, v0
	s_nop 4
	v_cndmask_b32_e32 v4, 0, v12, vcc
	v_cmp_le_i32_e32 vcc, v211, v32
	v_add_u32_e32 v8, v31, v16
	s_nop 0
	v_cndmask_b32_e32 v5, 0, v13, vcc
	v_cmp_lt_i32_e32 vcc, v1, v32
	s_nop 1
	v_cndmask_b32_e32 v6, 0, v14, vcc
	v_cmp_lt_i32_e32 vcc, v0, v32
	v_cvt_pk_bf16_f32 v0, v4, v5
	s_nop 0
	v_cndmask_b32_e32 v7, 0, v15, vcc
	v_cvt_pk_bf16_f32 v1, v6, v7
	s_and_b64 vcc, exec, s[0:1]
	ds_write_b64 v8, v[0:1]
	s_cbranch_vccnz .LBB0_750
	v_add_u32_e32 v0, s62, v2
	v_add_u32_e32 v0, 0x1e800, v0
	ds_write_b128 v0, v[4:7]
.LBB0_750:
	v_cndmask_b32_e64 v2, 0, 1, s[26:27]
	s_waitcnt lgkmcnt(0)
	s_barrier
	v_cmp_ne_u32_e64 s[0:1], 1, v2
	v_and_b32_e32 v0, 15, v28
	v_ashrrev_i32_e32 v1, 4, v28
	s_andn2_b64 vcc, exec, s[26:27]
	s_mov_b64 s[4:5], -1
	s_cbranch_vccnz .LBB0_764
	s_and_b64 vcc, exec, s[36:37]
	s_cbranch_vccz .LBB0_755
	v_readlane_b32 s4, v233, 43
	v_readlane_b32 s5, v233, 44
	s_andn2_b64 vcc, exec, s[4:5]
	s_cbranch_vccnz .LBB0_754
	v_and_b32_e32 v8, -16, v28
	v_mul_u32_u24_e32 v4, 0x90, v0
	s_add_i32 s4, 0, 0x14e00
	v_add3_u32 v29, s4, v4, v8
	ds_read_b128 v[4:7], v134
	v_or_b32_e32 v2, s63, v0
	v_mul_lo_u32 v2, v2, s76
	ds_read_b128 v[8:11], v134 offset:64
	ds_read_b128 v[12:15], v132 offset:64512
	ds_read_b128 v[16:19], v132 offset:64576
	s_add_i32 s4, 0, 0x1ce00
	v_lshlrev_b32_e32 v30, 3, v1
	s_waitcnt lgkmcnt(1)
	v_mfma_f32_16x16x32_bf16 v[4:7], v[4:7], v[12:15], 0
	v_add3_u32 v2, s4, v2, v30
	s_waitcnt lgkmcnt(0)
	v_mfma_f32_16x16x32_bf16 v[4:7], v[8:11], v[16:19], v[4:7]
	s_nop 7
	v_cvt_pk_bf16_f32 v4, v4, v5
	v_cvt_pk_bf16_f32 v5, v6, v7
	ds_write_b64 v138, v[4:5]
	ds_read_b128 v[4:7], v134 offset:2304
	ds_read_b128 v[8:11], v134 offset:2368
	s_waitcnt lgkmcnt(1)
	v_mfma_f32_16x16x32_bf16 v[4:7], v[4:7], v[12:15], 0
	s_waitcnt lgkmcnt(0)
	v_mfma_f32_16x16x32_bf16 v[4:7], v[8:11], v[16:19], v[4:7]
	s_nop 7
	v_cvt_pk_bf16_f32 v4, v4, v5
	v_cvt_pk_bf16_f32 v5, v6, v7
	ds_write_b64 v138, v[4:5] offset:32
	ds_read_b128 v[4:7], v134 offset:4608
	ds_read_b128 v[8:11], v134 offset:4672
	s_waitcnt lgkmcnt(1)
	v_mfma_f32_16x16x32_bf16 v[4:7], v[4:7], v[12:15], 0
	s_waitcnt lgkmcnt(0)
	v_mfma_f32_16x16x32_bf16 v[4:7], v[8:11], v[16:19], v[4:7]
	s_nop 7
	v_cvt_pk_bf16_f32 v4, v4, v5
	v_cvt_pk_bf16_f32 v5, v6, v7
	ds_write_b64 v138, v[4:5] offset:64
	ds_read_b128 v[4:7], v134 offset:6912
	ds_read_b128 v[8:11], v134 offset:6976
	s_waitcnt lgkmcnt(1)
	v_mfma_f32_16x16x32_bf16 v[4:7], v[4:7], v[12:15], 0
	s_waitcnt lgkmcnt(0)
	v_mfma_f32_16x16x32_bf16 v[4:7], v[8:11], v[16:19], v[4:7]
	s_nop 7
	v_cvt_pk_bf16_f32 v4, v4, v5
	v_cvt_pk_bf16_f32 v5, v6, v7
	ds_write_b64 v138, v[4:5] offset:96

.LBB0_755:
	s_andn2_b64 vcc, exec, s[4:5]
	s_cbranch_vccnz .LBB0_763
	v_mul_lo_u32 v2, v28, s76
	v_cmp_lt_u32_e32 vcc, 15, v28
	v_add_u32_e32 v2, 0, v2
	s_and_saveexec_b64 s[4:5], vcc
	s_cbranch_execz .LBB0_758
	s_mov_b32 s17, s16
	s_mov_b32 s18, s16
	s_mov_b32 s19, s16
	v_mov_b64_e32 v[4:5], s[16:17]
	v_mov_b64_e32 v[6:7], s[18:19]
	ds_write_b128 v147, v[4:7]
	ds_write_b128 v147, v[4:7] offset:16
.LBB0_758:
	s_or_b64 exec, exec, s[4:5]
	v_cmp_eq_u32_e64 s[8:9], 1, v1
	v_cmp_ne_u32_e32 vcc, 1, v1
	s_mov_b64 s[6:7], 0
	s_and_saveexec_b64 s[46:47], vcc
	s_cbranch_execz .LBB0_769
	s_mov_b32 s17, s16
	v_cmp_ne_u32_e64 s[4:5], 2, v162
	s_mov_b32 s18, s16
	s_mov_b32 s19, s16
	v_mov_b64_e32 v[4:5], s[16:17]
	v_cmp_eq_u32_e32 vcc, 2, v162
	s_andn2_b64 s[8:9], s[8:9], exec
	s_and_b64 s[4:5], s[4:5], exec
	v_mov_b64_e32 v[6:7], s[18:19]
	s_and_b64 s[6:7], vcc, exec
	s_or_b64 s[8:9], s[8:9], s[4:5]
	ds_write_b128 v147, v[4:7] offset:32
	ds_write_b128 v147, v[4:7] offset:48
	s_or_b64 exec, exec, s[46:47]
	s_and_saveexec_b64 s[4:5], s[8:9]
	s_cbranch_execnz .LBB0_770

.LBB0_761:
	s_mov_b32 s17, s16
	s_mov_b32 s18, s16
	s_mov_b32 s19, s16
	v_mov_b64_e32 v[4:5], s[16:17]
	v_mov_b64_e32 v[6:7], s[18:19]
	ds_write_b128 v147, v[4:7] offset:96
	ds_write_b128 v147, v[4:7] offset:112

.LBB0_764:
	s_andn2_b64 vcc, exec, s[4:5]
	s_cbranch_vccnz .LBB0_766
	v_cmp_eq_u32_e32 vcc, 0, v0
	s_movk_i32 s4, 0x500
	v_mul_lo_u32 v2, v1, s4
	v_cndmask_b32_e64 v30, 0, 1.0, vcc
	v_cmp_eq_u32_e32 vcc, 1, v0
	s_movk_i32 s4, 0x300
	s_nop 0
	v_cndmask_b32_e64 v31, 0, 1.0, vcc
	v_cmp_eq_u32_e32 vcc, 2, v0
	s_nop 1
	v_cndmask_b32_e64 v32, 0, 1.0, vcc
	v_cmp_eq_u32_e32 vcc, 3, v0
	s_nop 1
	v_cndmask_b32_e64 v33, 0, 1.0, vcc
	v_cmp_eq_u32_e32 vcc, 4, v0
	s_nop 1
	v_cndmask_b32_e64 v34, 0, 1.0, vcc
	v_cmp_eq_u32_e32 vcc, 5, v0
	s_nop 1
	v_cndmask_b32_e64 v35, 0, 1.0, vcc
	v_cmp_eq_u32_e32 vcc, 6, v0
	s_nop 1
	v_cndmask_b32_e64 v90, 0, 1.0, vcc
	v_cmp_eq_u32_e32 vcc, 7, v0
	s_nop 1
	v_cndmask_b32_e64 v91, 0, 1.0, vcc
	v_cmp_eq_u32_e32 vcc, 8, v0
	s_nop 1
	v_cndmask_b32_e64 v92, 0, 1.0, vcc
	v_cmp_eq_u32_e32 vcc, 9, v0
	s_nop 1
	v_cndmask_b32_e64 v93, 0, 1.0, vcc
	v_cmp_eq_u32_e32 vcc, 10, v0
	s_nop 1
	v_cndmask_b32_e64 v94, 0, 1.0, vcc
	v_cmp_eq_u32_e32 vcc, 11, v0
	s_nop 1
	v_cndmask_b32_e64 v95, 0, 1.0, vcc
	v_cmp_eq_u32_e32 vcc, 12, v0
	s_nop 1
	v_cndmask_b32_e64 v96, 0, 1.0, vcc
	v_cmp_eq_u32_e32 vcc, 13, v0
	s_nop 1
	v_cndmask_b32_e64 v97, 0, 1.0, vcc
	v_cmp_eq_u32_e32 vcc, 14, v0
	s_nop 1
	v_cndmask_b32_e64 v98, 0, 1.0, vcc
	v_mul_lo_u32 v1, v1, s4
	s_add_i32 s4, 0, 0x1ba00
	v_bfi_b32 v4, v165, v81, v80
	v_add3_u32 v2, 0, v2, v4
	ds_read_b128 v[4:7], v205
	ds_read_b128 v[8:11], v205 offset:16
	ds_read_b128 v[12:15], v205 offset:32
	ds_read_b128 v[16:19], v205 offset:48
	v_cmp_eq_u32_e32 vcc, 15, v0
	s_waitcnt lgkmcnt(2)
	v_pk_fma_f32 v[34:35], v[30:31], v[8:9], v[34:35] op_sel_hi:[0,1,1]
	s_waitcnt lgkmcnt(1)
	v_pk_fma_f32 v[92:93], v[30:31], v[12:13], v[92:93] op_sel_hi:[0,1,1]
	v_pk_fma_f32 v[100:101], v[30:31], v[4:5], v[30:31] op_sel_hi:[0,1,1]
	v_pk_fma_f32 v[32:33], v[30:31], v[6:7], v[32:33] op_sel_hi:[0,1,1]
	v_pk_fma_f32 v[90:91], v[30:31], v[10:11], v[90:91] op_sel_hi:[0,1,1]
	v_pk_fma_f32 v[94:95], v[30:31], v[14:15], v[94:95] op_sel_hi:[0,1,1]
	s_waitcnt lgkmcnt(0)
	v_pk_fma_f32 v[16:17], v[30:31], v[16:17], v[96:97] op_sel_hi:[0,1,1]
	ds_read_b64 v[96:97], v205 offset:88
	ds_read_b128 v[4:7], v205 offset:96
	ds_read_b128 v[8:11], v205 offset:112
	ds_read_b128 v[12:15], v205 offset:128
	v_cndmask_b32_e64 v99, 0, 1.0, vcc
	v_pk_fma_f32 v[18:19], v[30:31], v[18:19], v[98:99] op_sel_hi:[0,1,1]
	s_waitcnt lgkmcnt(3)
	v_pk_fma_f32 v[30:31], v[100:101], v[96:97], v[32:33] op_sel:[1,0,0]
	s_waitcnt lgkmcnt(2)
	v_pk_fma_f32 v[32:33], v[100:101], v[4:5], v[34:35] op_sel:[1,0,0]
	s_waitcnt lgkmcnt(0)
	v_pk_fma_f32 v[16:17], v[100:101], v[12:13], v[16:17] op_sel:[1,0,0]
	v_pk_fma_f32 v[34:35], v[100:101], v[6:7], v[90:91] op_sel:[1,0,0]
	v_pk_fma_f32 v[90:91], v[100:101], v[8:9], v[92:93] op_sel:[1,0,0]
	v_pk_fma_f32 v[92:93], v[100:101], v[10:11], v[94:95] op_sel:[1,0,0]
	ds_read_b64 v[94:95], v205 offset:168
	ds_read_b128 v[4:7], v205 offset:176
	v_pk_fma_f32 v[18:19], v[100:101], v[14:15], v[18:19] op_sel:[1,0,0]
	ds_read_b128 v[8:11], v205 offset:192
	ds_read_b128 v[12:15], v205 offset:208
	s_waitcnt lgkmcnt(3)
	v_pk_fma_f32 v[94:95], v[30:31], v[94:95], v[30:31] op_sel_hi:[0,1,1]
	s_waitcnt lgkmcnt(2)
	v_pk_fma_f32 v[32:33], v[30:31], v[4:5], v[32:33] op_sel_hi:[0,1,1]
	v_pk_fma_f32 v[34:35], v[30:31], v[6:7], v[34:35] op_sel_hi:[0,1,1]
	s_waitcnt lgkmcnt(1)
	v_pk_fma_f32 v[90:91], v[30:31], v[8:9], v[90:91] op_sel_hi:[0,1,1]
	v_pk_fma_f32 v[92:93], v[30:31], v[10:11], v[92:93] op_sel_hi:[0,1,1]
	ds_read_b128 v[4:7], v205 offset:256
	ds_read_b128 v[8:11], v205 offset:272
	s_waitcnt lgkmcnt(2)
	v_pk_fma_f32 v[16:17], v[30:31], v[12:13], v[16:17] op_sel_hi:[0,1,1]
	v_pk_fma_f32 v[18:19], v[30:31], v[14:15], v[18:19] op_sel_hi:[0,1,1]
	ds_read_b128 v[12:15], v205 offset:288
	s_waitcnt lgkmcnt(2)
	v_pk_fma_f32 v[30:31], v[94:95], v[4:5], v[32:33] op_sel:[1,0,0]
	v_pk_fma_f32 v[32:33], v[94:95], v[6:7], v[34:35] op_sel:[1,0,0]
	s_waitcnt lgkmcnt(1)
	v_pk_fma_f32 v[34:35], v[94:95], v[8:9], v[90:91] op_sel:[1,0,0]
	v_pk_fma_f32 v[90:91], v[94:95], v[10:11], v[92:93] op_sel:[1,0,0]
	ds_read_b128 v[4:7], v205 offset:336
	ds_read_b128 v[8:11], v205 offset:352
	s_waitcnt lgkmcnt(2)
	v_pk_fma_f32 v[16:17], v[94:95], v[12:13], v[16:17] op_sel:[1,0,0]
	v_pk_fma_f32 v[18:19], v[94:95], v[14:15], v[18:19] op_sel:[1,0,0]
	ds_read_b128 v[12:15], v205 offset:368
	s_waitcnt lgkmcnt(2)
	v_pk_fma_f32 v[92:93], v[30:31], v[4:5], v[30:31] op_sel_hi:[0,1,1]
	s_waitcnt lgkmcnt(1)
	v_pk_fma_f32 v[34:35], v[30:31], v[8:9], v[34:35] op_sel_hi:[0,1,1]
	v_pk_fma_f32 v[32:33], v[30:31], v[6:7], v[32:33] op_sel_hi:[0,1,1]
	ds_read_b64 v[96:97], v205 offset:424
	ds_read_b128 v[4:7], v205 offset:432
	v_mov_b32_e32 v29, v2
	v_pk_fma_f32 v[90:91], v[30:31], v[10:11], v[90:91] op_sel_hi:[0,1,1]
	ds_read_b128 v[8:11], v205 offset:448
	s_waitcnt lgkmcnt(3)
	v_pk_fma_f32 v[12:13], v[30:31], v[12:13], v[16:17] op_sel_hi:[0,1,1]
	v_pk_fma_f32 v[14:15], v[30:31], v[14:15], v[18:19] op_sel_hi:[0,1,1]
	s_waitcnt lgkmcnt(2)
	v_pk_fma_f32 v[16:17], v[92:93], v[96:97], v[32:33] op_sel:[1,0,0]
	s_waitcnt lgkmcnt(1)
	v_pk_fma_f32 v[18:19], v[92:93], v[4:5], v[34:35] op_sel:[1,0,0]
	v_pk_fma_f32 v[30:31], v[92:93], v[6:7], v[90:91] op_sel:[1,0,0]
	ds_read_b64 v[32:33], v205 offset:504
	ds_read_b128 v[4:7], v205 offset:512
	s_waitcnt lgkmcnt(2)
	v_pk_fma_f32 v[34:35], v[92:93], v[8:9], v[12:13] op_sel:[1,0,0]
	v_pk_fma_f32 v[90:91], v[92:93], v[10:11], v[14:15] op_sel:[1,0,0]
	ds_read_b128 v[8:11], v205 offset:528
	s_waitcnt lgkmcnt(2)
	v_pk_fma_f32 v[32:33], v[16:17], v[32:33], v[16:17] op_sel_hi:[0,1,1]
	s_waitcnt lgkmcnt(1)
	v_pk_fma_f32 v[18:19], v[16:17], v[4:5], v[18:19] op_sel_hi:[0,1,1]
	ds_read_b128 v[12:15], v205 offset:592
	v_pk_fma_f32 v[30:31], v[16:17], v[6:7], v[30:31] op_sel_hi:[0,1,1]
	ds_read_b128 v[4:7], v205 offset:608
	s_waitcnt lgkmcnt(2)
	v_pk_fma_f32 v[34:35], v[16:17], v[8:9], v[34:35] op_sel_hi:[0,1,1]
	v_pk_fma_f32 v[16:17], v[16:17], v[10:11], v[90:91] op_sel_hi:[0,1,1]
	s_waitcnt lgkmcnt(1)
	v_pk_fma_f32 v[18:19], v[32:33], v[12:13], v[18:19] op_sel:[1,0,0]
	ds_read_b128 v[8:11], v205 offset:672
	s_waitcnt lgkmcnt(1)
	v_pk_fma_f32 v[34:35], v[32:33], v[4:5], v[34:35] op_sel:[1,0,0]
	v_pk_fma_f32 v[16:17], v[32:33], v[6:7], v[16:17] op_sel:[1,0,0]
	ds_read_b128 v[4:7], v205 offset:688
	v_pk_fma_f32 v[30:31], v[32:33], v[14:15], v[30:31] op_sel:[1,0,0]
	s_waitcnt lgkmcnt(1)
	v_pk_fma_f32 v[90:91], v[18:19], v[8:9], v[18:19] op_sel_hi:[0,1,1]
	ds_read_b64 v[8:9], v205 offset:760
	ds_read_b128 v[12:15], v205 offset:768
	s_waitcnt lgkmcnt(2)
	v_pk_fma_f32 v[4:5], v[18:19], v[4:5], v[34:35] op_sel_hi:[0,1,1]
	v_pk_fma_f32 v[10:11], v[18:19], v[10:11], v[30:31] op_sel_hi:[0,1,1]
	v_pk_fma_f32 v[16:17], v[18:19], v[6:7], v[16:17] op_sel_hi:[0,1,1]
	s_waitcnt lgkmcnt(1)
	v_pk_fma_f32 v[18:19], v[90:91], v[8:9], v[10:11] op_sel:[1,0,0]
	s_waitcnt lgkmcnt(0)
	v_pk_fma_f32 v[12:13], v[90:91], v[12:13], v[4:5] op_sel:[1,0,0]
	ds_read_b64 v[30:31], v205 offset:840
	ds_read_b128 v[4:7], v205 offset:848
	ds_read_b128 v[8:11], v205 offset:928
	v_pk_fma_f32 v[14:15], v[90:91], v[14:15], v[16:17] op_sel:[1,0,0]
	s_waitcnt lgkmcnt(2)
	v_pk_fma_f32 v[16:17], v[18:19], v[30:31], v[18:19] op_sel_hi:[0,1,1]
	s_waitcnt lgkmcnt(1)
	v_pk_fma_f32 v[4:5], v[18:19], v[4:5], v[12:13] op_sel_hi:[0,1,1]
	v_pk_fma_f32 v[12:13], v[18:19], v[6:7], v[14:15] op_sel_hi:[0,1,1]
	s_waitcnt lgkmcnt(0)
	v_pk_fma_f32 v[8:9], v[16:17], v[8:9], v[4:5] op_sel:[1,0,0]
	ds_read_b128 v[4:7], v205 offset:1008
	ds_read_b64 v[14:15], v205 offset:1096
	ds_read_b64 v[18:19], v2 offset:1176
	v_pk_fma_f32 v[10:11], v[16:17], v[10:11], v[12:13] op_sel:[1,0,0]
	s_waitcnt lgkmcnt(2)
	v_pk_fma_f32 v[12:13], v[4:5], v[8:9], v[8:9] op_sel_hi:[1,0,1]
	v_pk_fma_f32 v[4:5], v[6:7], v[8:9], v[10:11] op_sel_hi:[1,0,1]
	v_and_b32_e32 v2, 0xffffff0, v28
	s_waitcnt lgkmcnt(1)
	v_pk_fma_f32 v[4:5], v[14:15], v[12:13], v[4:5] op_sel:[0,1,0]
	v_mul_lo_u32 v2, v2, s76
	s_waitcnt lgkmcnt(0)
	v_pk_fma_f32 v[14:15], v[18:19], v[4:5], v[4:5] op_sel_hi:[1,0,1]
	v_lshlrev_b32_e32 v5, 1, v28
	v_mul_u32_u24_e32 v0, 48, v0
	v_cvt_pk_bf16_f32 v4, v100, v101
	v_add3_u32 v2, 0, v2, v5
	v_cvt_pk_bf16_f32 v5, v94, v95
	v_cvt_pk_bf16_f32 v6, v92, v93
	v_cvt_pk_bf16_f32 v7, v32, v33
	v_cvt_pk_bf16_f32 v8, v90, v91
	v_cvt_pk_bf16_f32 v9, v16, v17
	v_cvt_pk_bf16_f32 v10, v12, v13
	v_cvt_pk_bf16_f32 v11, v14, v15
	v_add3_u32 v0, s4, v1, v0
	ds_write_b16 v131, v4
	ds_write_b16_d16_hi v131, v4 offset:144
	ds_write_b16 v131, v5 offset:288
	ds_write_b16_d16_hi v131, v5 offset:432
	ds_write_b16 v131, v6 offset:576
	ds_write_b16_d16_hi v131, v6 offset:720
	ds_write_b16 v131, v7 offset:864
	ds_write_b16_d16_hi v131, v7 offset:1008
	ds_write_b16 v131, v8 offset:1152
	ds_write_b16_d16_hi v131, v8 offset:1296
	ds_write_b16 v131, v9 offset:1440
	ds_write_b16_d16_hi v131, v9 offset:1584
	ds_write_b16 v131, v10 offset:1728
	ds_write_b16_d16_hi v131, v10 offset:1872
	ds_write_b16 v131, v11 offset:2016
	ds_write_b16_d16_hi v131, v11 offset:2160
	ds_write_b128 v135, v[4:7]
	ds_write_b128 v135, v[8:11] offset:16

.LBB0_770:
	s_mov_b32 s17, s16
	v_cmp_ne_u32_e32 vcc, 3, v162
	s_mov_b32 s18, s16
	s_mov_b32 s19, s16
	v_mov_b64_e32 v[4:5], s[16:17]
	s_andn2_b64 s[6:7], s[6:7], exec
	s_and_b64 s[8:9], vcc, exec
	v_mov_b64_e32 v[6:7], s[18:19]
	s_or_b64 s[6:7], s[6:7], s[8:9]
	ds_write_b128 v147, v[4:7] offset:64
	ds_write_b128 v147, v[4:7] offset:80
	s_or_b64 exec, exec, s[4:5]
	s_and_saveexec_b64 s[4:5], s[6:7]
	s_cbranch_execnz .LBB0_761
	s_branch .LBB0_762

.LBB0_772:
	v_or_b32_e32 v0, s88, v161
	v_mul_lo_u32 v0, v0, s76
	v_add3_u32 v0, s48, v0, v160
	ds_read_b128 v[8:11], v0 offset:64
	v_readlane_b32 s4, v233, 54
	s_nop 1
	v_or_b32_e32 v0, s4, v161
	v_mul_lo_u32 v13, v0, s76
	v_add3_u32 v0, 0, v13, v160
	ds_read_b128 v[14:17], v0 offset:64
	s_mov_b64 s[4:5], 0
	s_waitcnt lgkmcnt(0)
	v_mfma_f32_16x16x32_bf16 v[8:11], v[8:11], v[14:17], v[4:7]
.LBB0_773:
	s_andn2_b64 vcc, exec, s[4:5]
	s_cbranch_vccnz .LBB0_775
	s_nop 5
	v_mov_b64_e32 v[10:11], v[6:7]
	v_mad_u32_u24 v13, v161, s76, v82
	v_mov_b64_e32 v[8:9], v[4:5]
.LBB0_775:
	v_ashrrev_i32_e32 v1, 1, v207
	v_mul_u32_u24_e32 v0, 48, v161
	v_and_b32_e32 v12, -8, v1
	v_add3_u32 v0, s64, v0, v12
	ds_read_b64 v[4:5], v0
	v_mov_b32_e32 v6, v3
	v_mov_b32_e32 v7, v3
	v_cvt_pk_bf16_f32 v0, v8, v9
	v_cvt_pk_bf16_f32 v1, v10, v11
	v_mov_b32_e32 v2, v3
	s_waitcnt lgkmcnt(0)
	s_nop 0
	v_mfma_f32_16x16x32_bf16 v[4:7], v[4:7], v[0:3], 0
	v_add_u32_e32 v2, 0, v13
	v_add3_u32 v2, v2, v12, s65
	s_nop 5
	v_cvt_pk_bf16_f32 v0, v4, v5
	v_cvt_pk_bf16_f32 v1, v6, v7
	ds_write_b64 v2, v[0:1]
.LBB0_776:
	s_andn2_b64 vcc, exec, s[28:29]
	s_waitcnt lgkmcnt(0)
	s_barrier
	s_cbranch_vccnz .LBB0_782
	s_mov_b64 s[4:5], -1
	s_and_b64 vcc, exec, s[0:1]
	v_and_b32_e32 v2, -16, v207
	s_cbranch_vccnz .LBB0_779
	v_and_b32_e32 v1, -16, v207
	s_mov_b64 s[4:5], 0
.LBB0_779:
	v_and_b32_e32 v0, 15, v207
	v_mov_b32_e32 v4, 0
	s_andn2_b64 vcc, exec, s[4:5]
	v_mov_b32_e32 v5, 0
	v_mov_b32_e32 v6, 0
	v_mov_b32_e32 v7, 0
	s_cbranch_vccnz .LBB0_781
	v_mul_u32_u24_e32 v1, 0x90, v0
	v_add3_u32 v4, s48, v1, v2
	ds_read_b128 v[4:7], v4
	v_add3_u32 v1, 0, v1, v2
	ds_read_b128 v[8:11], v1 offset:4608
	v_mov_b32_e32 v1, v2
	s_waitcnt lgkmcnt(0)
	v_mfma_f32_16x16x32_bf16 v[4:7], v[4:7], v[8:11], 0
.LBB0_781:
	v_or_b32_e32 v2, s88, v0
	v_mul_lo_u32 v2, v2, s76
	v_add_u32_e32 v29, 0, v2
	v_add3_u32 v8, s48, v2, v1
	v_add_u32_e32 v1, v29, v1
	ds_read_b128 v[8:11], v8 offset:64
	ds_read_b128 v[12:15], v1 offset:4672
	v_ashrrev_i32_e32 v1, 1, v207
	v_mul_u32_u24_e32 v0, 48, v0
	v_and_b32_e32 v30, -8, v1
	v_add3_u32 v0, s64, v0, v30
	ds_read_b64 v[16:17], v0
	v_mov_b32_e32 v18, v3
	v_mov_b32_e32 v19, v3
	s_waitcnt lgkmcnt(1)
	v_mfma_f32_16x16x32_bf16 v[4:7], v[8:11], v[12:15], v[4:7]
	v_mov_b32_e32 v2, v3
	s_nop 6
	v_cvt_pk_bf16_f32 v0, v4, v5
	v_cvt_pk_bf16_f32 v1, v6, v7
	s_waitcnt lgkmcnt(0)
	s_nop 0
	v_mfma_f32_16x16x32_bf16 v[4:7], v[16:19], v[0:3], 0
	v_add3_u32 v2, v29, v30, s65
	s_nop 6
	v_cvt_pk_bf16_f32 v0, v4, v5
	v_cvt_pk_bf16_f32 v1, v6, v7
	ds_write_b64 v2, v[0:1] offset:4608
.LBB0_782:
	s_and_b64 vcc, exec, s[22:23]
	s_waitcnt lgkmcnt(0)
	s_barrier
	s_cbranch_vccnz .LBB0_784
	v_and_b32_e32 v0, 15, v207
	v_mul_u32_u24_e32 v1, 0x90, v0
	v_and_b32_e32 v2, -16, v207
	v_add3_u32 v1, s48, v1, v2
	ds_read_b128 v[4:7], v1
	v_mad_u32_u24 v29, v0, s76, 0
	v_add_u32_e32 v2, v29, v2
	ds_read_b128 v[8:11], v2 offset:6912
	ds_read_b128 v[12:15], v1 offset:64
	v_ashrrev_i32_e32 v30, 1, v207
	v_mul_u32_u24_e32 v0, 48, v0
	v_and_b32_e32 v30, -8, v30
	ds_read_b128 v[16:19], v2 offset:6976
	v_add3_u32 v0, s64, v0, v30
	s_waitcnt lgkmcnt(2)
	v_mfma_f32_16x16x32_bf16 v[4:7], v[4:7], v[8:11], 0
	ds_read_b64 v[8:9], v0
	v_mov_b32_e32 v10, v3
	v_mov_b32_e32 v11, v3
	s_waitcnt lgkmcnt(1)
	v_mfma_f32_16x16x32_bf16 v[4:7], v[12:15], v[16:19], v[4:7]
	v_mov_b32_e32 v2, v3
	s_nop 6
	v_cvt_pk_bf16_f32 v0, v4, v5
	v_cvt_pk_bf16_f32 v1, v6, v7
	s_waitcnt lgkmcnt(0)
	s_nop 0
	v_mfma_f32_16x16x32_bf16 v[4:7], v[8:11], v[0:3], 0
	v_add3_u32 v2, v29, v30, s65
	s_nop 6
	v_cvt_pk_bf16_f32 v0, v4, v5
	v_cvt_pk_bf16_f32 v1, v6, v7
	ds_write_b64 v2, v[0:1] offset:6912
.LBB0_784:
	s_cmpk_gt_i32 s79, 0xfff
	s_waitcnt lgkmcnt(0)
	s_barrier
	s_cbranch_scc1 .LBB0_789
	s_and_b32 s4, s79, 0x7f
	s_ashr_i32 s0, s79, 11
	s_ashr_i32 s1, s0, 31
	s_lshl_b32 s5, s4, 6
	s_lshl_b64 s[0:1], s[0:1], 13
	s_add_i32 s5, s5, s33
	s_add_u32 s6, s0, s5
	s_addc_u32 s7, s1, 0
	s_lshr_b32 s0, s79, 1
	s_and_b32 s0, s0, 0x3c0
	v_add_u32_e32 v2, s0, v207
	s_mul_i32 s0, s7, 0x3c00
	s_mul_hi_u32 s1, s6, 0x3c00
	s_add_i32 s1, s1, s0
	s_mul_i32 s0, s6, 0x3c00
	v_readlane_b32 s8, v233, 14
	v_readlane_b32 s9, v233, 15
	s_add_u32 s0, s8, s0
	s_addc_u32 s1, s9, s1
	s_lshl_b64 s[6:7], s[6:7], 10
	v_add_u32_e32 v4, 0x400, v2
	v_mov_b32_e32 v5, v3
	v_add_u32_e32 v0, 0x800, v2
	v_mov_b32_e32 v1, v3
	v_lshl_add_u64 v[8:9], s[6:7], 0, v[2:3]
	s_add_u32 s6, s0, 0x3c00
	v_lshlrev_b64 v[6:7], 1, v[2:3]
	v_lshlrev_b64 v[10:11], 1, v[4:5]
	v_lshlrev_b64 v[12:13], 1, v[0:1]
	v_lshlrev_b64 v[8:9], 1, v[8:9]
	v_readlane_b32 s8, v233, 24
	s_addc_u32 s7, s1, 0
	v_lshl_add_u64 v[14:15], s[0:1], 0, v[6:7]
	v_lshl_add_u64 v[24:25], s[2:3], 0, v[8:9]
	v_readlane_b32 s9, v233, 25
	v_lshl_add_u64 v[32:33], s[6:7], 0, v[6:7]
	v_lshl_add_u64 v[34:35], s[6:7], 0, v[10:11]
	v_lshl_add_u64 v[40:41], s[6:7], 0, v[12:13]
	s_mov_b64 s[6:7], 0x800
	v_lshl_add_u64 v[16:17], s[0:1], 0, v[10:11]
	v_lshl_add_u64 v[18:19], s[0:1], 0, v[12:13]
	v_lshl_add_u64 v[30:31], s[8:9], 0, v[8:9]
	global_load_ushort v37, v[14:15], off
	global_load_ushort v27, v[16:17], off
	global_load_ushort v45, v[18:19], off
	global_load_ushort v36, v[24:25], off
	s_nop 0
	global_load_ushort v25, v[30:31], off
	global_load_ushort v39, v[32:33], off
	global_load_ushort v38, v[34:35], off
	global_load_ushort v47, v[40:41], off
	v_lshl_add_u64 v[14:15], v[8:9], 0, s[6:7]
	s_add_u32 s6, s0, 0x7800
	s_addc_u32 s7, s1, 0
	v_lshl_add_u64 v[18:19], s[6:7], 0, v[6:7]
	v_lshl_add_u64 v[30:31], s[6:7], 0, v[10:11]
	v_lshl_add_u64 v[32:33], s[6:7], 0, v[12:13]
	s_mov_b64 s[6:7], 0x1000
	v_lshl_add_u64 v[34:35], v[8:9], 0, s[6:7]
	s_add_u32 s6, s0, 0xb400
	v_lshl_add_u64 v[16:17], s[2:3], 0, v[14:15]
	v_lshl_add_u64 v[14:15], s[8:9], 0, v[14:15]
	v_lshl_add_u64 v[48:49], s[2:3], 0, v[34:35]
	s_addc_u32 s7, s1, 0
	v_lshl_add_u64 v[34:35], s[8:9], 0, v[34:35]
	v_lshl_add_u64 v[50:51], s[6:7], 0, v[6:7]
	global_load_ushort v41, v[16:17], off
	global_load_ushort v40, v[14:15], off
	global_load_ushort v46, v[18:19], off
	global_load_ushort v43, v[30:31], off
	global_load_ushort v52, v[32:33], off
	global_load_ushort v44, v[48:49], off
	global_load_ushort v42, v[34:35], off
	s_nop 0
	global_load_ushort v48, v[50:51], off
	v_lshl_add_u64 v[14:15], s[6:7], 0, v[10:11]
	v_lshl_add_u64 v[16:17], s[6:7], 0, v[12:13]
	s_mov_b64 s[6:7], 0x1800
	v_lshl_add_u64 v[18:19], v[8:9], 0, s[6:7]
	s_add_u32 s6, s0, 0xf000
	s_addc_u32 s7, s1, 0
	v_lshl_add_u64 v[32:33], s[6:7], 0, v[6:7]
	v_lshl_add_u64 v[34:35], s[6:7], 0, v[10:11]
	v_lshl_add_u64 v[56:57], s[6:7], 0, v[12:13]
	s_mov_b64 s[6:7], 0x2000
	v_lshl_add_u64 v[58:59], v[8:9], 0, s[6:7]
	s_add_u32 s6, s0, 0x12c00
	v_lshl_add_u64 v[30:31], s[2:3], 0, v[18:19]
	v_lshl_add_u64 v[18:19], s[8:9], 0, v[18:19]
	s_addc_u32 s7, s1, 0
	v_lshl_add_u64 v[60:61], s[2:3], 0, v[58:59]
	global_load_ushort v50, v[14:15], off
	global_load_ushort v54, v[16:17], off
	global_load_ushort v51, v[30:31], off
	global_load_ushort v49, v[18:19], off
	global_load_ushort v55, v[32:33], off
	global_load_ushort v53, v[34:35], off
	s_nop 0
	global_load_ushort v56, v[56:57], off
	s_nop 0
	global_load_ushort v57, v[60:61], off
	v_lshl_add_u64 v[16:17], s[6:7], 0, v[6:7]
	v_lshl_add_u64 v[18:19], s[6:7], 0, v[10:11]
	v_lshl_add_u64 v[30:31], s[6:7], 0, v[12:13]
	s_mov_b64 s[6:7], 0x2800
	v_lshl_add_u64 v[32:33], v[8:9], 0, s[6:7]
	s_add_u32 s6, s0, 0x16800
	s_addc_u32 s7, s1, 0
	v_lshl_add_u64 v[14:15], s[8:9], 0, v[58:59]
	v_lshl_add_u64 v[64:65], s[6:7], 0, v[6:7]
	v_lshl_add_u64 v[34:35], s[2:3], 0, v[32:33]
	v_lshl_add_u64 v[32:33], s[8:9], 0, v[32:33]
	v_lshl_add_u64 v[66:67], s[6:7], 0, v[10:11]
	global_load_ushort v58, v[14:15], off
	global_load_ushort v62, v[16:17], off
	global_load_ushort v59, v[18:19], off
	global_load_ushort v61, v[30:31], off
	global_load_ushort v63, v[34:35], off
	global_load_ushort v60, v[32:33], off
	s_nop 0
	global_load_ushort v64, v[64:65], off
	s_nop 0
	global_load_ushort v65, v[66:67], off
	v_lshl_add_u64 v[14:15], s[6:7], 0, v[12:13]
	s_mov_b64 s[6:7], 0x3000
	v_lshl_add_u64 v[16:17], v[8:9], 0, s[6:7]
	s_add_u32 s6, s0, 0x1a400
	s_addc_u32 s7, s1, 0
	v_lshl_add_u64 v[6:7], s[6:7], 0, v[6:7]
	v_lshl_add_u64 v[10:11], s[6:7], 0, v[10:11]
	v_lshl_add_u64 v[12:13], s[6:7], 0, v[12:13]
	s_mov_b64 s[6:7], 0x3800
	v_lshl_add_u64 v[18:19], s[2:3], 0, v[16:17]
	v_lshl_add_u64 v[16:17], s[8:9], 0, v[16:17]
	global_load_ushort v66, v[14:15], off
	global_load_ushort v68, v[18:19], off
	global_load_ushort v67, v[16:17], off
	global_load_ushort v72, v[6:7], off
	global_load_ushort v70, v[10:11], off
	global_load_ushort v71, v[12:13], off
	v_lshl_add_u64 v[6:7], v[8:9], 0, s[6:7]
	v_lshl_add_u64 v[8:9], s[2:3], 0, v[6:7]
	v_lshl_add_u64 v[6:7], s[8:9], 0, v[6:7]
	global_load_ushort v74, v[8:9], off
	global_load_ushort v73, v[6:7], off
	v_readlane_b32 s5, v233, 5
	s_or_b32 s4, s4, s5
	s_cmp_eq_u32 s4, 0
	s_cbranch_scc1 .LBB0_787
	s_add_u32 s0, s0, 0xffffc400
	s_addc_u32 s1, s1, -1
	v_lshl_add_u64 v[10:11], v[2:3], 1, s[0:1]
	v_lshl_add_u64 v[6:7], v[0:1], 1, s[0:1]
	v_lshl_add_u64 v[8:9], v[4:5], 1, s[0:1]
	global_load_ushort v75, v[10:11], off
	global_load_ushort v76, v[8:9], off
	global_load_ushort v88, v[6:7], off
	s_branch .LBB0_788

.LBB0_789:
	v_and_b32_e32 v0, 15, v207
	v_or_b32_e32 v1, s68, v0
	v_and_b32_e32 v2, -16, v207
	v_mul_u32_u24_e32 v0, 0x90, v0
	v_add3_u32 v29, 0, v0, v2
	ds_read_b128 v[4:7], v29
	v_mul_u32_u24_e32 v0, 0x90, v1
	v_add3_u32 v1, s66, v0, v2
	ds_read_b128 v[8:11], v29 offset:64
	ds_read_b128 v[12:15], v1
	ds_read_b128 v[16:19], v1 offset:64
	v_ashrrev_i32_e32 v1, 1, v207
	v_and_b32_e32 v1, -8, v1
	v_add3_u32 v2, s67, v0, v1
	s_waitcnt lgkmcnt(1)
	v_mfma_f32_16x16x32_bf16 v[4:7], v[4:7], v[12:15], 0
	v_readlane_b32 s4, v233, 43
	v_readlane_b32 s5, v233, 44
	s_mov_b64 s[0:1], -1
	s_waitcnt lgkmcnt(0)
	v_mfma_f32_16x16x32_bf16 v[4:7], v[8:11], v[16:19], v[4:7]
	s_and_b64 vcc, exec, s[4:5]
	s_nop 6
	v_cvt_pk_bf16_f32 v0, v4, v5
	v_cvt_pk_bf16_f32 v1, v6, v7
	ds_write_b64 v2, v[0:1]
	ds_read_b128 v[4:7], v29 offset:2304
	ds_read_b128 v[8:11], v29 offset:2368
	s_waitcnt lgkmcnt(1)
	v_mfma_f32_16x16x32_bf16 v[4:7], v[4:7], v[12:15], 0
	s_waitcnt lgkmcnt(0)
	v_mfma_f32_16x16x32_bf16 v[4:7], v[8:11], v[16:19], v[4:7]
	s_nop 7
	v_cvt_pk_bf16_f32 v0, v4, v5
	v_cvt_pk_bf16_f32 v1, v6, v7
	ds_write_b64 v2, v[0:1] offset:32
	ds_read_b128 v[4:7], v29 offset:4608
	ds_read_b128 v[8:11], v29 offset:4672
	s_waitcnt lgkmcnt(1)
	v_mfma_f32_16x16x32_bf16 v[4:7], v[4:7], v[12:15], 0
	s_waitcnt lgkmcnt(0)
	v_mfma_f32_16x16x32_bf16 v[4:7], v[8:11], v[16:19], v[4:7]
	s_nop 7
	v_cvt_pk_bf16_f32 v0, v4, v5
	v_cvt_pk_bf16_f32 v1, v6, v7
	ds_write_b64 v2, v[0:1] offset:64
	ds_read_b128 v[4:7], v29 offset:6912
	ds_read_b128 v[8:11], v29 offset:6976
	s_waitcnt lgkmcnt(1)
	v_mfma_f32_16x16x32_bf16 v[4:7], v[4:7], v[12:15], 0
	s_waitcnt lgkmcnt(0)
	v_mfma_f32_16x16x32_bf16 v[4:7], v[8:11], v[16:19], v[4:7]
	s_nop 7
	v_cvt_pk_bf16_f32 v0, v4, v5
	v_cvt_pk_bf16_f32 v1, v6, v7
	ds_write_b64 v2, v[0:1] offset:96
	s_waitcnt lgkmcnt(0)
	s_barrier
	s_nop 0
	v_and_b32_e32 v7, 15, v207
	v_ashrrev_i32_e32 v1, 4, v207
	v_and_b32_e32 v0, -16, v207
	v_lshlrev_b32_e32 v5, 3, v1
	v_mul_u32_u24_e32 v6, 0x90, v7
	v_mad_u32_u24 v4, v7, s76, v82
	v_mad_u32_u24 v2, v7, s76, v83
	v_mad_u32_u24 v1, v7, s76, v87
	s_cbranch_vccz .LBB0_791
	v_or_b32_e32 v8, s63, v7
	v_mul_lo_u32 v8, v8, s76
	v_add_u32_e32 v89, s69, v5
	v_add3_u32 v29, 0, v8, v0
	v_add3_u32 v30, 0, v89, v6
	ds_read_b128 v[8:11], v29 offset:18432
	ds_read_b128 v[12:15], v29 offset:18496
	ds_read_b64 v[32:33], v30 offset:9216
	s_add_i32 s0, 0, 0x17200
	v_add_u32_e32 v98, s0, v0
	v_mad_u32_u24 v99, v7, s76, v98
	ds_read_b128 v[16:19], v99
	ds_read_b64 v[34:35], v30 offset:11520
	ds_read_b64 v[94:95], v30 offset:13824
	ds_read_b64 v[96:97], v30 offset:16128
	s_waitcnt lgkmcnt(4)
	v_lshlrev_b32_e32 v30, 16, v32
	v_and_b32_e32 v31, 0xffff0000, v32
	v_lshlrev_b32_e32 v32, 16, v33
	v_and_b32_e32 v33, 0xffff0000, v33
	ds_read_b128 v[90:93], v99 offset:64
	s_add_i32 s1, 0, 0x14e00
	s_waitcnt lgkmcnt(4)
	v_mfma_f32_16x16x32_bf16 v[16:19], v[8:11], v[16:19], v[30:33]
	v_add3_u32 v89, s1, v89, v6
	v_add_u32_e32 v102, v98, v4
	v_add3_u32 v103, s0, v4, v0
	s_waitcnt lgkmcnt(0)
	v_mfma_f32_16x16x32_bf16 v[16:19], v[12:15], v[90:93], v[16:19]
	v_lshlrev_b32_e32 v30, 16, v34
	v_and_b32_e32 v31, 0xffff0000, v34
	v_lshlrev_b32_e32 v32, 16, v35
	v_and_b32_e32 v33, 0xffff0000, v35
	v_add_u32_e32 v34, v98, v2
	s_nop 2
	v_cvt_pk_bf16_f32 v16, v16, v17
	v_cvt_pk_bf16_f32 v17, v18, v19
	ds_write_b64 v89, v[16:17]
	ds_read_b128 v[16:19], v102
	ds_read_b128 v[90:93], v103 offset:64
	s_waitcnt lgkmcnt(1)
	v_mfma_f32_16x16x32_bf16 v[16:19], v[8:11], v[16:19], v[30:33]
	v_add3_u32 v35, s0, v2, v0
	s_nop 1
	v_lshlrev_b32_e32 v30, 16, v94
	v_and_b32_e32 v31, 0xffff0000, v94
	s_waitcnt lgkmcnt(0)
	v_mfma_f32_16x16x32_bf16 v[16:19], v[12:15], v[90:93], v[16:19]
	v_lshlrev_b32_e32 v32, 16, v95
	v_and_b32_e32 v33, 0xffff0000, v95
	v_add_u32_e32 v104, v98, v1
	v_add3_u32 v105, s0, v1, v0
	s_add_i32 s0, 0, 0x19600
	s_nop 2
	v_cvt_pk_bf16_f32 v16, v16, v17
	v_cvt_pk_bf16_f32 v17, v18, v19
	ds_write_b64 v89, v[16:17] offset:2304
	ds_read_b128 v[16:19], v34
	ds_read_b128 v[90:93], v35 offset:64
	s_waitcnt lgkmcnt(1)
	v_mfma_f32_16x16x32_bf16 v[16:19], v[8:11], v[16:19], v[30:33]
	s_nop 2
	v_lshlrev_b32_e32 v30, 16, v96
	v_and_b32_e32 v31, 0xffff0000, v96
	v_lshlrev_b32_e32 v32, 16, v97
	s_waitcnt lgkmcnt(0)
	v_mfma_f32_16x16x32_bf16 v[16:19], v[12:15], v[90:93], v[16:19]
	v_and_b32_e32 v33, 0xffff0000, v97
	s_nop 6
	v_cvt_pk_bf16_f32 v16, v16, v17
	v_cvt_pk_bf16_f32 v17, v18, v19
	ds_write_b64 v89, v[16:17] offset:4608
	ds_read_b128 v[16:19], v104
	ds_read_b128 v[90:93], v105 offset:64
	s_waitcnt lgkmcnt(1)
	v_mfma_f32_16x16x32_bf16 v[8:11], v[8:11], v[16:19], v[30:33]
	s_waitcnt lgkmcnt(0)
	v_mfma_f32_16x16x32_bf16 v[8:11], v[12:15], v[90:93], v[8:11]
	s_nop 7
	v_cvt_pk_bf16_f32 v8, v8, v9
	v_cvt_pk_bf16_f32 v9, v10, v11
	ds_write_b64 v89, v[8:9] offset:6912
	ds_read_b128 v[8:11], v29 offset:27648
	ds_read_b128 v[12:15], v29 offset:27712
	ds_read_b128 v[16:19], v99
	ds_read_b128 v[30:33], v99 offset:64
	ds_read_b128 v[90:93], v29 offset:64512
	ds_read_b128 v[94:97], v29 offset:64576
	s_waitcnt lgkmcnt(3)
	v_mfma_f32_16x16x32_bf16 v[16:19], v[8:11], v[16:19], 0
	v_add_u32_e32 v89, s0, v0
	v_mad_u32_u24 v98, v7, s76, v89
	v_add3_u32 v29, s70, v5, v6
	s_waitcnt lgkmcnt(2)
	v_mfma_f32_16x16x32_bf16 v[16:19], v[12:15], v[30:33], v[16:19]
	ds_read_b128 v[30:33], v98
	ds_read_b128 v[98:101], v98 offset:64
	s_waitcnt lgkmcnt(1)
	v_mfma_f32_16x16x32_bf16 v[16:19], v[90:93], v[30:33], v[16:19]
	s_waitcnt lgkmcnt(0)
	v_mfma_f32_16x16x32_bf16 v[16:19], v[94:97], v[98:101], v[16:19]
	v_add_u32_e32 v98, v89, v4
	s_nop 6
	v_cvt_pk_bf16_f32 v16, v16, v17
	v_cvt_pk_bf16_f32 v17, v18, v19
	ds_write_b64 v29, v[16:17]
	ds_read_b128 v[16:19], v102
	ds_read_b128 v[30:33], v103 offset:64
	s_waitcnt lgkmcnt(1)
	v_mfma_f32_16x16x32_bf16 v[16:19], v[8:11], v[16:19], 0
	s_waitcnt lgkmcnt(0)
	v_mfma_f32_16x16x32_bf16 v[16:19], v[12:15], v[30:33], v[16:19]
	ds_read_b128 v[30:33], v98
	v_add3_u32 v98, s0, v4, v0
	ds_read_b128 v[98:101], v98 offset:64
	s_waitcnt lgkmcnt(1)
	v_mfma_f32_16x16x32_bf16 v[16:19], v[90:93], v[30:33], v[16:19]
	s_waitcnt lgkmcnt(0)
	v_mfma_f32_16x16x32_bf16 v[16:19], v[94:97], v[98:101], v[16:19]
	s_nop 7
	v_cvt_pk_bf16_f32 v16, v16, v17
	v_cvt_pk_bf16_f32 v17, v18, v19
	ds_write_b64 v29, v[16:17] offset:2304
	ds_read_b128 v[16:19], v34
	ds_read_b128 v[30:33], v35 offset:64
	s_waitcnt lgkmcnt(1)
	v_mfma_f32_16x16x32_bf16 v[16:19], v[8:11], v[16:19], 0
	v_add_u32_e32 v34, v89, v2
	s_waitcnt lgkmcnt(0)
	v_mfma_f32_16x16x32_bf16 v[16:19], v[12:15], v[30:33], v[16:19]
	ds_read_b128 v[30:33], v34
	v_add3_u32 v34, s0, v2, v0
	ds_read_b128 v[98:101], v34 offset:64
	s_waitcnt lgkmcnt(1)
	v_mfma_f32_16x16x32_bf16 v[16:19], v[90:93], v[30:33], v[16:19]
	s_waitcnt lgkmcnt(0)
	v_mfma_f32_16x16x32_bf16 v[16:19], v[94:97], v[98:101], v[16:19]
	s_nop 7
	v_cvt_pk_bf16_f32 v16, v16, v17
	v_cvt_pk_bf16_f32 v17, v18, v19
	ds_write_b64 v29, v[16:17] offset:4608
	ds_read_b128 v[16:19], v104
	ds_read_b128 v[30:33], v105 offset:64
	s_waitcnt lgkmcnt(1)
	v_mfma_f32_16x16x32_bf16 v[8:11], v[8:11], v[16:19], 0
	v_add_u32_e32 v16, v89, v1
	s_waitcnt lgkmcnt(0)
	v_mfma_f32_16x16x32_bf16 v[8:11], v[12:15], v[30:33], v[8:11]
	ds_read_b128 v[12:15], v16
	v_add3_u32 v16, s0, v1, v0
	ds_read_b128 v[16:19], v16 offset:64
	s_waitcnt lgkmcnt(1)
	v_mfma_f32_16x16x32_bf16 v[8:11], v[90:93], v[12:15], v[8:11]
	s_mov_b64 s[0:1], 0
	s_waitcnt lgkmcnt(0)
	v_mfma_f32_16x16x32_bf16 v[8:11], v[94:97], v[16:19], v[8:11]
	s_nop 7
	v_cvt_pk_bf16_f32 v8, v8, v9
	v_cvt_pk_bf16_f32 v9, v10, v11
	ds_write_b64 v29, v[8:9] offset:6912
